# adds GEMM accumulator zeroing via 64 v_mov_b64 (was 128 v_mov_b32) and single vmcnt wait before K/V staging ds_writes
# baseline (speedup 1.0000x reference)
;     __device__ bool next(int i, Unit& u) const { if (i > 0) return false; u.pm = pm; u.pn = pn; return true; }
; template <class Epi, class Sched, bool ALIGN_EPI = false, bool SP2 = false>
; __device__ __forceinline__ void gemm_phase(PG8_LAS unsigned char* lds, const Gemm g, const Sched& S, const Epi& E) {
;     ...
;         const bool has_next = S.next(ui + 1, nxt);
;         const char* nA = has_next ? (const char*)g.A + (size_t)nxt.pm * tstep : cA; const char* nB = has_next ? (const char*)g.Bt + (size_t)nxt.pn * tstep : cB;
;         for (int t = 0; t < nt; t += 2) {
;             const bool last = (t == nt - 2);
;             const char* a1 = cA + (size_t)(t + 1) * kstep;
;             const char* a2 = last ? nA : cA + (size_t)(t + 2) * kstep; const char* b2 = last ? nB : cB + (size_t)(t + 2) * kstep;
;     ...
; #pragma unroll
;         for (int a = 0; a < 2; ++a)
; #pragma unroll
;             for (int b = 0; b < 2; ++b)
; #pragma unroll
;                 for (int m = 0; m < 4; ++m)
; #pragma unroll
;                     for (int n = 0; n < 2; ++n) acc[a][b][m][n] = (f32x4){0.f, 0.f, 0.f, 0.f};
.LBB0_172:
	s_ashr_i32 s17, s16, 31
	s_lshl_b64 s[18:19], s[16:17], 19
	s_add_u32 s18, s60, s18
	s_addc_u32 s19, s61, s19
	s_and_b64 s[20:21], s[4:5], exec
	s_cselect_b32 s17, s19, s7
	s_cselect_b32 s24, s18, s6
	s_ashr_i32 s15, s14, 31
	s_lshl_b64 s[20:21], s[14:15], 19
	s_add_u32 s20, s52, s20
	s_addc_u32 s21, s53, s21
	s_and_b64 s[22:23], s[4:5], exec
	s_cselect_b32 s15, s21, s9
	s_cselect_b32 s25, s20, s8
	s_add_u32 s6, s6, 0x40080
	s_addc_u32 s7, s7, 0
	s_add_u32 s26, s8, 0x100
	s_addc_u32 s27, s9, 0
	s_mov_b32 s28, -2
	v_mov_b64_e32 v[0:1], 0
	v_mov_b64_e32 v[2:3], 0
	v_mov_b64_e32 v[4:5], 0
	v_mov_b64_e32 v[6:7], 0
	v_mov_b64_e32 v[8:9], 0
	v_mov_b64_e32 v[10:11], 0
	v_mov_b64_e32 v[12:13], 0
	v_mov_b64_e32 v[14:15], 0
	v_mov_b64_e32 v[16:17], 0
	v_mov_b64_e32 v[18:19], 0
	v_mov_b64_e32 v[20:21], 0
	v_mov_b64_e32 v[22:23], 0
	v_mov_b64_e32 v[24:25], 0
	v_mov_b64_e32 v[26:27], 0
	v_mov_b64_e32 v[28:29], 0
	v_mov_b64_e32 v[30:31], 0
	v_mov_b64_e32 v[32:33], 0
	v_mov_b64_e32 v[34:35], 0
	v_mov_b64_e32 v[36:37], 0
	v_mov_b64_e32 v[38:39], 0
	v_mov_b64_e32 v[40:41], 0
	v_mov_b64_e32 v[42:43], 0
	v_mov_b64_e32 v[44:45], 0
	v_mov_b64_e32 v[46:47], 0
	v_mov_b64_e32 v[48:49], 0
	v_mov_b64_e32 v[50:51], 0
	v_mov_b64_e32 v[52:53], 0
	v_mov_b64_e32 v[54:55], 0
	v_mov_b64_e32 v[56:57], 0
	v_mov_b64_e32 v[58:59], 0
	v_mov_b64_e32 v[60:61], 0
	v_mov_b64_e32 v[62:63], 0
	v_mov_b64_e32 v[64:65], 0
	v_mov_b64_e32 v[66:67], 0
	v_mov_b64_e32 v[68:69], 0
	v_mov_b64_e32 v[70:71], 0
	v_mov_b64_e32 v[72:73], 0
	v_mov_b64_e32 v[74:75], 0
	v_mov_b64_e32 v[76:77], 0
	v_mov_b64_e32 v[78:79], 0
	v_mov_b64_e32 v[80:81], 0
	v_mov_b64_e32 v[82:83], 0
	v_mov_b64_e32 v[84:85], 0
	v_mov_b64_e32 v[86:87], 0
	v_mov_b64_e32 v[88:89], 0
	v_mov_b64_e32 v[90:91], 0
	v_mov_b64_e32 v[92:93], 0
	v_mov_b64_e32 v[94:95], 0
	v_mov_b64_e32 v[96:97], 0
	v_mov_b64_e32 v[98:99], 0
	v_mov_b64_e32 v[100:101], 0
	v_mov_b64_e32 v[102:103], 0
	v_mov_b64_e32 v[104:105], 0
	v_mov_b64_e32 v[106:107], 0
	v_mov_b64_e32 v[108:109], 0
	v_mov_b64_e32 v[110:111], 0
	v_mov_b64_e32 v[112:113], 0
	v_mov_b64_e32 v[114:115], 0
	v_mov_b64_e32 v[116:117], 0
	v_mov_b64_e32 v[118:119], 0
	v_mov_b64_e32 v[120:121], 0
	v_mov_b64_e32 v[122:123], 0
	v_mov_b64_e32 v[124:125], 0
	v_mov_b64_e32 v[126:127], 0

; template <int DV, int PAR, bool KW = true, bool KL = true, bool VL = true>
; __device__ __forceinline__ void attn_iter_full(AttnState<DV>& S, int t, LAS unsigned char* lds) {
;     constexpr int NDB = DV / 32, NS = 8 + 4 * NDB, NU = 27;
;     const LAS unsigned char* BK = lds + AT_K0 + (PAR ^ 1) * AT_KB + S.koff;
;     const LAS unsigned char* BV = lds + AT_V0 + PAR * AT_VB + S.voff;
;     f32x16& C0 = PAR ? S.sd0 : S.sc0; f32x16& C1 = PAR ? S.sd1 : S.sc1; f32x16& sn0 = PAR ? S.sc0 : S.sd0; f32x16& sn1 = PAR ? S.sc1 : S.sd1;
;     sn0 = S.negm; sn1 = S.negm;
;     u32x4 pw[4]; float mxa = 0.f, mxb = 0.f, mx = 0.f; f32x16 ssum;
;     constexpr int PD = (DV == 64) ? 3 : 2; bf16x8 fr[PD + 1];
;     ...
; #pragma unroll
;     for (int i = 0; i < PD; ++i) fr[i] = AT_FRAG(i);
;     __builtin_amdgcn_sched_barrier(0);
; #pragma unroll
;     for (int i = 0; i < NS; ++i) {
;         if (i + PD < NS) fr[(i + PD) % (PD + 1)] = AT_FRAG(i + PD);
;         if (i == 3) {
;             if (KW) *(LAS u32x4*)(lds + AT_K0 + PAR * AT_KB + S.kl) = S.kreg;
;             LAS unsigned char* W = lds + AT_V0 + (PAR ^ 1) * AT_VB + S.vl; *(LAS u32x4*)W = S.vreg0; if (DV == 128) *(LAS u32x4*)(W + 64 * 144) = S.vreg1; }
;         if (i == 5) { if (KL) S.kreg = *(const u32x4*)(S.kg + (size_t)(t + 3) * 4096);
;             if (VL) { S.vreg0 = *(const u32x4*)(S.vg + (t + 2) * 64); if (DV == 128) S.vreg1 = *(const u32x4*)(S.vg + (size_t)64 * TK + (t + 2) * 64); } }
;         if (i < 8) { if (i & 1) sn1 = MFMA32(fr[i % (PD + 1)], S.qr[i >> 1], sn1); else sn0 = MFMA32(fr[i % (PD + 1)], S.qr[i >> 1], sn0); }
;         else { const int j = i - 8; S.o[j % NDB] = MFMA32(fr[i % (PD + 1)], __builtin_bit_cast(bf16x8, pw[j / NDB]), S.o[j % NDB]); }
; #pragma unroll
;         for (int u = 0; u < NU; ++u) {
;             if (u * NS / NU != i) continue;
;             if (u < 20) {
;                 const int q = u / 5, r = u % 5;
;                 if (r < 4) { const int e = 8 * q + 2 * r;
;                     if (e < 16) { C0[e] = fast_exp2(C0[e]); C0[e + 1] = fast_exp2(C0[e + 1]); }
;                     else { C1[e - 16] = fast_exp2(C1[e - 16]); C1[e - 15] = fast_exp2(C1[e - 15]); } }
;                 else { if (q < 2) { const int b0 = 8 * q; pw[q].x = pk2(C0[b0], C0[b0 + 1]); pw[q].y = pk2(C0[b0 + 2], C0[b0 + 3]); pw[q].z = pk2(C0[b0 + 4], C0[b0 + 5]); pw[q].w = pk2(C0[b0 + 6], C0[b0 + 7]); }
.LBB0_397:
	ds_read_b128 v[32:35], v169 offset:9216
	ds_read_b128 v[36:39], v169 offset:13824
	ds_read_b128 v[40:43], v169 offset:9248
	s_waitcnt lgkmcnt(2)
	v_mfma_f32_32x32x16_bf16 v[112:127], v[32:35], v[140:143], v[64:79]
	ds_read_b128 v[44:47], v169 offset:13856
	v_exp_f32_e32 v32, v82
	v_exp_f32_e32 v34, v80
	v_exp_f32_e32 v35, v81
	v_exp_f32_e32 v33, v83
	s_waitcnt lgkmcnt(2)
	v_mfma_f32_32x32x16_bf16 v[96:111], v[36:39], v[140:143], v[64:79]
	ds_read_b128 v[80:83], v169 offset:9280
	v_exp_f32_e32 v38, v84
	v_exp_f32_e32 v39, v85
	v_exp_f32_e32 v36, v86
	v_exp_f32_e32 v37, v87
	s_waitcnt lgkmcnt(2)
	v_mfma_f32_32x32x16_bf16 v[112:127], v[40:43], v[136:139], v[112:127]
	ds_read_b128 v[84:87], v169 offset:13888
	v_cvt_pk_bf16_f32 v40, v34, v35
	v_cvt_pk_bf16_f32 v41, v32, v33
	v_cvt_pk_bf16_f32 v42, v38, v39
	v_cvt_pk_bf16_f32 v43, v36, v37
	v_exp_f32_e32 v176, v88
	v_exp_f32_e32 v177, v89
	s_waitcnt lgkmcnt(2)
	v_mfma_f32_32x32x16_bf16 v[96:111], v[44:47], v[136:139], v[96:111]
	ds_read_b128 v[172:175], v169 offset:9312
	s_waitcnt vmcnt(0)
	ds_write_b128 v168, v[144:147]
	ds_write_b128 v168, v[148:151] offset:36864
	v_exp_f32_e32 v178, v90
	v_exp_f32_e32 v179, v91
	s_waitcnt lgkmcnt(4)
	v_mfma_f32_32x32x16_bf16 v[112:127], v[80:83], v[132:135], v[112:127]
	ds_read_b128 v[44:47], v169 offset:13920
	v_exp_f32_e32 v92, v92
	v_exp_f32_e32 v93, v93
	v_exp_f32_e32 v94, v94
	v_exp_f32_e32 v95, v95
	ds_read_b128 v[80:83], v167 offset:18432
	global_load_dwordx4 v[144:147], v[156:157], off
	global_load_dwordx4 v[148:151], v[158:159], off offset:256
	s_waitcnt lgkmcnt(5)
	v_mfma_f32_32x32x16_bf16 v[96:111], v[84:87], v[132:135], v[96:111]
	v_cvt_pk_bf16_f32 v84, v176, v177
	v_exp_f32_e32 v180, v48
	v_exp_f32_e32 v181, v49
	v_cvt_pk_bf16_f32 v85, v178, v179
	v_cvt_pk_bf16_f32 v86, v92, v93
	v_cvt_pk_bf16_f32 v87, v94, v95
	s_waitcnt lgkmcnt(4)
	v_mfma_f32_32x32x16_bf16 v[112:127], v[172:175], v[128:131], v[112:127]
	ds_read_b128 v[88:91], v167 offset:23040
	v_exp_f32_e32 v172, v50
	v_exp_f32_e32 v173, v51
	s_waitcnt lgkmcnt(2)
	v_mfma_f32_32x32x16_bf16 v[96:111], v[44:47], v[128:131], v[96:111]
	ds_read_b128 v[48:51], v167 offset:18464
	v_exp_f32_e32 v174, v52
	v_exp_f32_e32 v175, v53
	v_exp_f32_e32 v182, v54
	v_exp_f32_e32 v183, v55
	s_waitcnt lgkmcnt(2)
	v_mfma_f32_32x32x16_bf16 v[0:15], v[80:83], v[40:43], v[0:15]
	ds_read_b128 v[44:47], v167 offset:23072
	v_cvt_pk_bf16_f32 v52, v180, v181
	v_cvt_pk_bf16_f32 v53, v172, v173
	v_cvt_pk_bf16_f32 v54, v174, v175
	v_cvt_pk_bf16_f32 v55, v182, v183
	v_exp_f32_e32 v56, v56
	v_exp_f32_e32 v57, v57
	s_waitcnt lgkmcnt(2)
	v_mfma_f32_32x32x16_bf16 v[16:31], v[88:91], v[40:43], v[16:31]
	ds_read_b128 v[80:83], v167 offset:18496
	v_exp_f32_e32 v58, v58
	v_exp_f32_e32 v59, v59
	s_waitcnt lgkmcnt(2)
	v_mfma_f32_32x32x16_bf16 v[0:15], v[48:51], v[84:87], v[0:15]
	ds_read_b128 v[40:43], v167 offset:23104
	v_exp_f32_e32 v60, v60
	v_exp_f32_e32 v61, v61
	v_exp_f32_e32 v62, v62
	v_exp_f32_e32 v63, v63
	s_waitcnt lgkmcnt(2)
	v_mfma_f32_32x32x16_bf16 v[16:31], v[44:47], v[84:87], v[16:31]
	ds_read_b128 v[48:51], v167 offset:18528
	v_cvt_pk_bf16_f32 v44, v56, v57
	v_cvt_pk_bf16_f32 v45, v58, v59
	v_cvt_pk_bf16_f32 v46, v60, v61
	v_cvt_pk_bf16_f32 v47, v62, v63
	v_pk_add_f32 v[60:61], v[60:61], v[92:93]
	v_pk_add_f32 v[62:63], v[62:63], v[94:95]
	v_pk_add_f32 v[58:59], v[58:59], v[178:179]
	v_pk_add_f32 v[56:57], v[56:57], v[176:177]
	v_pk_add_f32 v[38:39], v[174:175], v[38:39]
	v_pk_add_f32 v[84:85], v[180:181], v[34:35]
	v_pk_add_f32 v[36:37], v[182:183], v[36:37]
	v_pk_add_f32 v[86:87], v[172:173], v[32:33]
	s_waitcnt lgkmcnt(2)
	v_mfma_f32_32x32x16_bf16 v[0:15], v[80:83], v[52:55], v[0:15]
	v_add_f32_e64 v36, v86, v36
	v_add_f32_e64 v37, v87, v37
	v_add_f32_e64 v38, v84, v38
	v_add_f32_e64 v39, v85, v39
	v_add_f32_e64 v36, v58, v36
	v_add_f32_e64 v37, v59, v37
	v_pk_add_f32 v[38:39], v[56:57], v[38:39]
	ds_read_b128 v[32:35], v167 offset:23136
	v_pk_add_f32 v[36:37], v[62:63], v[36:37]
	v_pk_add_f32 v[38:39], v[60:61], v[38:39]
	s_nop 0
	v_pk_mov_b32 v[56:57], v[38:39], v[36:37] op_sel:[1,0]
	v_mov_b32_e32 v39, v37
	v_pk_add_f32 v[36:37], v[56:57], v[38:39]
	s_nop 0
	v_add_f32_e32 v36, v36, v37
	v_add_f32_e32 v171, v171, v36
	s_waitcnt lgkmcnt(2)
	v_mfma_f32_32x32x16_bf16 v[16:31], v[40:43], v[52:55], v[16:31]
	v_max3_f32 v36, v112, v113, v96
	v_max3_f32 v37, v114, v115, v97
	v_max3_f32 v36, v36, v98, v99
	v_max3_f32 v37, v37, v118, v119
	v_max3_f32 v36, v36, v116, v117
	v_max3_f32 v37, v37, v102, v103
	v_max3_f32 v36, v36, v100, v101
	s_waitcnt lgkmcnt(1)
	v_mfma_f32_32x32x16_bf16 v[0:15], v[48:51], v[44:47], v[0:15]
	v_max3_f32 v36, v36, v120, v121
	v_max3_f32 v37, v37, v122, v123
	v_max3_f32 v36, v36, v104, v105
	v_max3_f32 v37, v37, v106, v107
	v_max3_f32 v36, v36, v124, v125
	v_max3_f32 v37, v37, v126, v127
	v_max3_f32 v36, v36, v108, v109
	v_max3_f32 v37, v37, v110, v111
	s_waitcnt lgkmcnt(0)
	v_mfma_f32_32x32x16_bf16 v[16:31], v[32:35], v[44:47], v[16:31]
	v_max_f32_e32 v32, v36, v37
	v_mov_b32_e32 v33, v32
	s_nop 1
	v_permlane32_swap_b32_e32 v32, v33
	v_max_f32_e32 v32, v32, v33
	s_nop 0
	v_cmp_lt_f32_e32 vcc, s3, v32
	s_cbranch_vccz .LBB0_399
; template <int DV, int PAR, bool KW = true, bool KL = true, bool VL = true>
; __device__ __forceinline__ void attn_iter_full(AttnState<DV>& S, int t, LAS unsigned char* lds) {
;     constexpr int NDB = DV / 32, NS = 8 + 4 * NDB, NU = 27;
;     const LAS unsigned char* BK = lds + AT_K0 + (PAR ^ 1) * AT_KB + S.koff;
;     const LAS unsigned char* BV = lds + AT_V0 + PAR * AT_VB + S.voff;
;     f32x16& C0 = PAR ? S.sd0 : S.sc0; f32x16& C1 = PAR ? S.sd1 : S.sc1; f32x16& sn0 = PAR ? S.sc0 : S.sd0; f32x16& sn1 = PAR ? S.sc1 : S.sd1;
;     sn0 = S.negm; sn1 = S.negm;
;     u32x4 pw[4]; float mxa = 0.f, mxb = 0.f, mx = 0.f; f32x16 ssum;
;     constexpr int PD = (DV == 64) ? 3 : 2; bf16x8 fr[PD + 1];
;     ...
; #pragma unroll
;     for (int i = 0; i < PD; ++i) fr[i] = AT_FRAG(i);
;     __builtin_amdgcn_sched_barrier(0);
; #pragma unroll
;     for (int i = 0; i < NS; ++i) {
;         if (i + PD < NS) fr[(i + PD) % (PD + 1)] = AT_FRAG(i + PD);
;         if (i == 3) {
;             if (KW) *(LAS u32x4*)(lds + AT_K0 + PAR * AT_KB + S.kl) = S.kreg;
;             LAS unsigned char* W = lds + AT_V0 + (PAR ^ 1) * AT_VB + S.vl; *(LAS u32x4*)W = S.vreg0; if (DV == 128) *(LAS u32x4*)(W + 64 * 144) = S.vreg1; }
;         if (i == 5) { if (KL) S.kreg = *(const u32x4*)(S.kg + (size_t)(t + 3) * 4096);
;             if (VL) { S.vreg0 = *(const u32x4*)(S.vg + (t + 2) * 64); if (DV == 128) S.vreg1 = *(const u32x4*)(S.vg + (size_t)64 * TK + (t + 2) * 64); } }
;         if (i < 8) { if (i & 1) sn1 = MFMA32(fr[i % (PD + 1)], S.qr[i >> 1], sn1); else sn0 = MFMA32(fr[i % (PD + 1)], S.qr[i >> 1], sn0); }
;         else { const int j = i - 8; S.o[j % NDB] = MFMA32(fr[i % (PD + 1)], __builtin_bit_cast(bf16x8, pw[j / NDB]), S.o[j % NDB]); }
; #pragma unroll
;         for (int u = 0; u < NU; ++u) {
;             if (u * NS / NU != i) continue;
;             if (u < 20) {
;                 const int q = u / 5, r = u % 5;
;                 if (r < 4) { const int e = 8 * q + 2 * r;
;                     if (e < 16) { C0[e] = fast_exp2(C0[e]); C0[e + 1] = fast_exp2(C0[e + 1]); }
;                     else { C1[e - 16] = fast_exp2(C1[e - 16]); C1[e - 15] = fast_exp2(C1[e - 15]); } }
;                 else { if (q < 2) { const int b0 = 8 * q; pw[q].x = pk2(C0[b0], C0[b0 + 1]); pw[q].y = pk2(C0[b0 + 2], C0[b0 + 3]); pw[q].z = pk2(C0[b0 + 4], C0[b0 + 5]); pw[q].w = pk2(C0[b0 + 6], C0[b0 + 7]); }
	v_max_f32_e32 v32, v32, v32
	v_max_f32_e32 v34, 0, v32
	v_exp_f32_e64 v36, -v34
	v_add_f32_e32 v170, v170, v34
	v_xor_b32_e32 v32, 0x80000000, v170
	v_pk_add_f32 v[112:113], v[112:113], v[34:35] op_sel_hi:[1,0] neg_lo:[0,1] neg_hi:[0,1]
	v_mul_f32_e32 v171, v171, v36
	v_pk_add_f32 v[96:97], v[96:97], v[34:35] op_sel_hi:[1,0] neg_lo:[0,1] neg_hi:[0,1]
	v_pk_add_f32 v[114:115], v[114:115], v[34:35] op_sel_hi:[1,0] neg_lo:[0,1] neg_hi:[0,1]
	v_pk_add_f32 v[98:99], v[98:99], v[34:35] op_sel_hi:[1,0] neg_lo:[0,1] neg_hi:[0,1]
	v_pk_add_f32 v[116:117], v[116:117], v[34:35] op_sel_hi:[1,0] neg_lo:[0,1] neg_hi:[0,1]
	v_pk_add_f32 v[100:101], v[100:101], v[34:35] op_sel_hi:[1,0] neg_lo:[0,1] neg_hi:[0,1]
	v_pk_add_f32 v[118:119], v[118:119], v[34:35] op_sel_hi:[1,0] neg_lo:[0,1] neg_hi:[0,1]
	v_pk_add_f32 v[102:103], v[102:103], v[34:35] op_sel_hi:[1,0] neg_lo:[0,1] neg_hi:[0,1]
	v_pk_add_f32 v[120:121], v[120:121], v[34:35] op_sel_hi:[1,0] neg_lo:[0,1] neg_hi:[0,1]
	v_pk_add_f32 v[104:105], v[104:105], v[34:35] op_sel_hi:[1,0] neg_lo:[0,1] neg_hi:[0,1]
	v_pk_add_f32 v[122:123], v[122:123], v[34:35] op_sel_hi:[1,0] neg_lo:[0,1] neg_hi:[0,1]
	v_pk_add_f32 v[106:107], v[106:107], v[34:35] op_sel_hi:[1,0] neg_lo:[0,1] neg_hi:[0,1]
	v_pk_add_f32 v[124:125], v[124:125], v[34:35] op_sel_hi:[1,0] neg_lo:[0,1] neg_hi:[0,1]
	v_pk_add_f32 v[108:109], v[108:109], v[34:35] op_sel_hi:[1,0] neg_lo:[0,1] neg_hi:[0,1]
	v_pk_add_f32 v[126:127], v[126:127], v[34:35] op_sel_hi:[1,0] neg_lo:[0,1] neg_hi:[0,1]
	v_pk_add_f32 v[110:111], v[110:111], v[34:35] op_sel_hi:[1,0] neg_lo:[0,1] neg_hi:[0,1]
	v_pk_mul_f32 v[14:15], v[14:15], v[36:37] op_sel_hi:[1,0]
	v_pk_mul_f32 v[12:13], v[12:13], v[36:37] op_sel_hi:[1,0]
	v_pk_mul_f32 v[10:11], v[10:11], v[36:37] op_sel_hi:[1,0]
	v_pk_mul_f32 v[8:9], v[8:9], v[36:37] op_sel_hi:[1,0]
	v_pk_mul_f32 v[6:7], v[6:7], v[36:37] op_sel_hi:[1,0]
	v_pk_mul_f32 v[4:5], v[4:5], v[36:37] op_sel_hi:[1,0]
	v_pk_mul_f32 v[2:3], v[2:3], v[36:37] op_sel_hi:[1,0]
	v_pk_mul_f32 v[0:1], v[0:1], v[36:37] op_sel_hi:[1,0]
	v_pk_mul_f32 v[30:31], v[30:31], v[36:37] op_sel_hi:[1,0]
	v_pk_mul_f32 v[28:29], v[28:29], v[36:37] op_sel_hi:[1,0]
	v_pk_mul_f32 v[26:27], v[26:27], v[36:37] op_sel_hi:[1,0]
	v_pk_mul_f32 v[24:25], v[24:25], v[36:37] op_sel_hi:[1,0]
	v_pk_mul_f32 v[22:23], v[22:23], v[36:37] op_sel_hi:[1,0]
	v_pk_mul_f32 v[20:21], v[20:21], v[36:37] op_sel_hi:[1,0]
	v_pk_mul_f32 v[18:19], v[18:19], v[36:37] op_sel_hi:[1,0]
	v_pk_mul_f32 v[16:17], v[16:17], v[36:37] op_sel_hi:[1,0]
	v_mov_b32_e32 v33, v32
	v_mov_b32_e32 v34, v32
	v_mov_b32_e32 v35, v32
	v_mov_b32_e32 v36, v32
	v_mov_b32_e32 v37, v32
	v_mov_b32_e32 v38, v32
	v_mov_b32_e32 v39, v32
	v_mov_b32_e32 v40, v32
	v_mov_b32_e32 v41, v32
	v_mov_b32_e32 v42, v32
	v_mov_b32_e32 v43, v32
	v_mov_b32_e32 v44, v32
	v_mov_b32_e32 v45, v32
	v_mov_b32_e32 v46, v32
	v_mov_b32_e32 v47, v32
	v_mov_b32_e32 v64, v32
	v_mov_b32_e32 v65, v32
	v_mov_b32_e32 v66, v32
	v_mov_b32_e32 v67, v32
	v_mov_b32_e32 v68, v32
	v_mov_b32_e32 v69, v32
	v_mov_b32_e32 v70, v32
	v_mov_b32_e32 v71, v32
	v_mov_b32_e32 v72, v32
	v_mov_b32_e32 v73, v32
	v_mov_b32_e32 v74, v32
	v_mov_b32_e32 v75, v32
	v_mov_b32_e32 v76, v32
	v_mov_b32_e32 v77, v32
	v_mov_b32_e32 v78, v32
	v_mov_b32_e32 v79, v32
	s_branch .LBB0_400
.LBB0_399:
.LBB0_400:
	s_barrier
	ds_read_b128 v[48:51], v169
	ds_read_b128 v[172:175], v169 offset:4608
	ds_read_b128 v[176:179], v169 offset:32
	s_waitcnt lgkmcnt(2)
	v_mfma_f32_32x32x16_bf16 v[80:95], v[48:51], v[140:143], v[64:79]
	ds_read_b128 v[180:183], v169 offset:4640
	v_exp_f32_e32 v184, v112
	v_exp_f32_e32 v185, v113
	v_exp_f32_e32 v186, v114
	v_exp_f32_e32 v187, v115
	s_waitcnt lgkmcnt(2)
	v_mfma_f32_32x32x16_bf16 v[48:63], v[172:175], v[140:143], v[64:79]
	ds_read_b128 v[112:115], v169 offset:64
	v_exp_f32_e32 v188, v116
	v_exp_f32_e32 v189, v117
	v_exp_f32_e32 v190, v118
	v_exp_f32_e32 v191, v119
	s_waitcnt lgkmcnt(2)
	v_mfma_f32_32x32x16_bf16 v[80:95], v[176:179], v[136:139], v[80:95]
	ds_read_b128 v[116:119], v169 offset:4672
	v_cvt_pk_bf16_f32 v172, v184, v185
	v_cvt_pk_bf16_f32 v173, v186, v187
	v_cvt_pk_bf16_f32 v174, v188, v189
	v_cvt_pk_bf16_f32 v175, v190, v191
	v_exp_f32_e32 v192, v120
	v_exp_f32_e32 v193, v121
	s_waitcnt lgkmcnt(2)
	v_mfma_f32_32x32x16_bf16 v[48:63], v[180:183], v[136:139], v[48:63]
	ds_read_b128 v[176:179], v169 offset:96
	s_waitcnt vmcnt(0)
	ds_write_b128 v168, v[144:147] offset:9216
	ds_write_b128 v168, v[148:151] offset:18432
	v_exp_f32_e32 v196, v122
	v_exp_f32_e32 v197, v123
	s_waitcnt lgkmcnt(4)
	v_mfma_f32_32x32x16_bf16 v[80:95], v[112:115], v[132:135], v[80:95]
	ds_read_b128 v[120:123], v169 offset:4704
	v_exp_f32_e32 v180, v124
	v_exp_f32_e32 v181, v125
	v_exp_f32_e32 v182, v126
	v_exp_f32_e32 v183, v127
	v_lshl_add_u64 v[124:125], v[156:157], 0, s[100:101]
	ds_read_b128 v[112:115], v167 offset:36864
	global_load_dwordx4 v[144:147], v[124:125], off
	global_load_dwordx4 v[148:151], v[158:159], off offset:384
	s_waitcnt lgkmcnt(5)
	v_mfma_f32_32x32x16_bf16 v[48:63], v[116:119], v[132:135], v[48:63]
	v_cvt_pk_bf16_f32 v116, v192, v193
	v_exp_f32_e32 v162, v96
	v_exp_f32_e32 v163, v97
	v_cvt_pk_bf16_f32 v117, v196, v197
	v_cvt_pk_bf16_f32 v118, v180, v181
	v_cvt_pk_bf16_f32 v119, v182, v183
	s_waitcnt lgkmcnt(4)
	v_mfma_f32_32x32x16_bf16 v[80:95], v[176:179], v[128:131], v[80:95]
	ds_read_b128 v[124:127], v167 offset:41472
	v_exp_f32_e32 v164, v98
	v_exp_f32_e32 v165, v99
	s_waitcnt lgkmcnt(2)
	v_mfma_f32_32x32x16_bf16 v[48:63], v[120:123], v[128:131], v[48:63]
	ds_read_b128 v[96:99], v167 offset:36896
	v_exp_f32_e32 v176, v100
	v_exp_f32_e32 v177, v101
	v_exp_f32_e32 v178, v102
	v_exp_f32_e32 v179, v103
	s_waitcnt lgkmcnt(2)
; template <int DV, int PAR, bool KW = true, bool KL = true, bool VL = true>
; __device__ __forceinline__ void attn_iter_full(AttnState<DV>& S, int t, LAS unsigned char* lds) {
;     constexpr int NDB = DV / 32, NS = 8 + 4 * NDB, NU = 27;
;     const LAS unsigned char* BK = lds + AT_K0 + (PAR ^ 1) * AT_KB + S.koff;
;     const LAS unsigned char* BV = lds + AT_V0 + PAR * AT_VB + S.voff;
;     f32x16& C0 = PAR ? S.sd0 : S.sc0; f32x16& C1 = PAR ? S.sd1 : S.sc1; f32x16& sn0 = PAR ? S.sc0 : S.sd0; f32x16& sn1 = PAR ? S.sc1 : S.sd1;
;     sn0 = S.negm; sn1 = S.negm;
;     u32x4 pw[4]; float mxa = 0.f, mxb = 0.f, mx = 0.f; f32x16 ssum;
;     constexpr int PD = (DV == 64) ? 3 : 2; bf16x8 fr[PD + 1];
;     ...
; #pragma unroll
;     for (int i = 0; i < PD; ++i) fr[i] = AT_FRAG(i);
;     __builtin_amdgcn_sched_barrier(0);
; #pragma unroll
;     for (int i = 0; i < NS; ++i) {
;         if (i + PD < NS) fr[(i + PD) % (PD + 1)] = AT_FRAG(i + PD);
;         if (i == 3) {
;             if (KW) *(LAS u32x4*)(lds + AT_K0 + PAR * AT_KB + S.kl) = S.kreg;
;             LAS unsigned char* W = lds + AT_V0 + (PAR ^ 1) * AT_VB + S.vl; *(LAS u32x4*)W = S.vreg0; if (DV == 128) *(LAS u32x4*)(W + 64 * 144) = S.vreg1; }
;         if (i == 5) { if (KL) S.kreg = *(const u32x4*)(S.kg + (size_t)(t + 3) * 4096);
;             if (VL) { S.vreg0 = *(const u32x4*)(S.vg + (t + 2) * 64); if (DV == 128) S.vreg1 = *(const u32x4*)(S.vg + (size_t)64 * TK + (t + 2) * 64); } }
;         if (i < 8) { if (i & 1) sn1 = MFMA32(fr[i % (PD + 1)], S.qr[i >> 1], sn1); else sn0 = MFMA32(fr[i % (PD + 1)], S.qr[i >> 1], sn0); }
;         else { const int j = i - 8; S.o[j % NDB] = MFMA32(fr[i % (PD + 1)], __builtin_bit_cast(bf16x8, pw[j / NDB]), S.o[j % NDB]); }
; #pragma unroll
;         for (int u = 0; u < NU; ++u) {
;             if (u * NS / NU != i) continue;
;             if (u < 20) {
;                 const int q = u / 5, r = u % 5;
;                 if (r < 4) { const int e = 8 * q + 2 * r;
;                     if (e < 16) { C0[e] = fast_exp2(C0[e]); C0[e + 1] = fast_exp2(C0[e + 1]); }
;                     else { C1[e - 16] = fast_exp2(C1[e - 16]); C1[e - 15] = fast_exp2(C1[e - 15]); } }
;                 else { if (q < 2) { const int b0 = 8 * q; pw[q].x = pk2(C0[b0], C0[b0 + 1]); pw[q].y = pk2(C0[b0 + 2], C0[b0 + 3]); pw[q].z = pk2(C0[b0 + 4], C0[b0 + 5]); pw[q].w = pk2(C0[b0 + 6], C0[b0 + 7]); }
	v_mfma_f32_32x32x16_bf16 v[0:15], v[112:115], v[172:175], v[0:15]
	ds_read_b128 v[100:103], v167 offset:41504
	v_cvt_pk_bf16_f32 v112, v162, v163
	v_cvt_pk_bf16_f32 v113, v164, v165
	v_cvt_pk_bf16_f32 v114, v176, v177
	v_cvt_pk_bf16_f32 v115, v178, v179
	v_exp_f32_e32 v198, v104
	v_exp_f32_e32 v199, v105
	s_waitcnt lgkmcnt(2)
	v_mfma_f32_32x32x16_bf16 v[16:31], v[124:127], v[172:175], v[16:31]
	ds_read_b128 v[120:123], v167 offset:36928
	v_exp_f32_e32 v124, v106
	v_exp_f32_e32 v125, v107
	s_waitcnt lgkmcnt(2)
	v_mfma_f32_32x32x16_bf16 v[0:15], v[96:99], v[116:119], v[0:15]
	ds_read_b128 v[104:107], v167 offset:41536
	v_exp_f32_e32 v108, v108
	v_exp_f32_e32 v109, v109
	v_exp_f32_e32 v110, v110
	v_exp_f32_e32 v111, v111
	s_waitcnt lgkmcnt(2)
	v_mfma_f32_32x32x16_bf16 v[16:31], v[100:103], v[116:119], v[16:31]
	ds_read_b128 v[96:99], v167 offset:36960
	v_cvt_pk_bf16_f32 v100, v198, v199
	v_cvt_pk_bf16_f32 v101, v124, v125
	v_cvt_pk_bf16_f32 v102, v108, v109
	v_cvt_pk_bf16_f32 v103, v110, v111
	v_pk_add_f32 v[116:117], v[108:109], v[180:181]
	v_pk_add_f32 v[118:119], v[110:111], v[182:183]
	v_pk_add_f32 v[124:125], v[124:125], v[196:197]
	v_pk_add_f32 v[126:127], v[198:199], v[192:193]
	v_pk_add_f32 v[172:173], v[176:177], v[188:189]
	v_pk_add_f32 v[162:163], v[162:163], v[184:185]
	v_pk_add_f32 v[174:175], v[178:179], v[190:191]
	v_pk_add_f32 v[164:165], v[164:165], v[186:187]
	s_waitcnt lgkmcnt(2)
	v_mfma_f32_32x32x16_bf16 v[0:15], v[120:123], v[112:115], v[0:15]
	v_add_f32_e64 v120, v164, v174
	v_add_f32_e64 v121, v165, v175
	v_add_f32_e64 v122, v162, v172
	v_add_f32_e64 v123, v163, v173
	v_add_f32_e64 v120, v124, v120
	v_add_f32_e64 v121, v125, v121
	v_pk_add_f32 v[122:123], v[126:127], v[122:123]
	v_pk_add_f32 v[118:119], v[118:119], v[120:121]
	v_pk_add_f32 v[116:117], v[116:117], v[122:123]
	ds_read_b128 v[108:111], v167 offset:41568
	v_pk_mov_b32 v[120:121], v[116:117], v[118:119] op_sel:[1,0]
	v_mov_b32_e32 v117, v119
	v_pk_add_f32 v[116:117], v[120:121], v[116:117]
	s_nop 0
	v_add_f32_e32 v116, v116, v117
	v_add_f32_e32 v171, v171, v116
	s_waitcnt lgkmcnt(2)
	v_mfma_f32_32x32x16_bf16 v[16:31], v[104:107], v[112:115], v[16:31]
	v_max3_f32 v104, v80, v81, v48
	v_max3_f32 v105, v82, v83, v49
	v_max3_f32 v104, v104, v50, v51
	v_max3_f32 v105, v105, v86, v87
	v_max3_f32 v104, v104, v84, v85
	v_max3_f32 v105, v105, v54, v55
	v_max3_f32 v104, v104, v52, v53
	s_waitcnt lgkmcnt(1)
	v_mfma_f32_32x32x16_bf16 v[0:15], v[96:99], v[100:103], v[0:15]
	v_max3_f32 v96, v104, v88, v89
	v_max3_f32 v97, v105, v90, v91
	v_max3_f32 v96, v96, v56, v57
	v_max3_f32 v97, v97, v58, v59
	v_max3_f32 v96, v96, v92, v93
	v_max3_f32 v97, v97, v94, v95
	v_max3_f32 v96, v96, v60, v61
	v_max3_f32 v97, v97, v62, v63
	s_waitcnt lgkmcnt(0)
	v_mfma_f32_32x32x16_bf16 v[16:31], v[108:111], v[100:103], v[16:31]
	v_max_f32_e32 v96, v96, v97
	v_mov_b32_e32 v97, v96
	s_nop 1
	v_permlane32_swap_b32_e32 v96, v97
	v_max_f32_e32 v96, v96, v97
	s_nop 0
	v_cmp_lt_f32_e32 vcc, s3, v96
	s_cbranch_vccz .LBB0_396
	v_max_f32_e32 v32, v96, v96
	v_max_f32_e32 v33, 0, v32
	v_exp_f32_e64 v34, -v33
	v_add_f32_e32 v170, v170, v33
	v_xor_b32_e32 v32, 0x80000000, v170
	v_sub_f32_e32 v95, v95, v33
	v_mul_f32_e32 v171, v171, v34
	v_sub_f32_e32 v94, v94, v33
	v_sub_f32_e32 v93, v93, v33
	v_sub_f32_e32 v92, v92, v33
	v_sub_f32_e32 v91, v91, v33
	v_sub_f32_e32 v90, v90, v33
	v_sub_f32_e32 v89, v89, v33
	v_sub_f32_e32 v88, v88, v33
	v_sub_f32_e32 v87, v87, v33
	v_sub_f32_e32 v86, v86, v33
	v_sub_f32_e32 v85, v85, v33
	v_sub_f32_e32 v84, v84, v33
	v_sub_f32_e32 v83, v83, v33
	v_sub_f32_e32 v82, v82, v33
	v_sub_f32_e32 v81, v81, v33
	v_sub_f32_e32 v80, v80, v33
	v_sub_f32_e32 v63, v63, v33
	v_sub_f32_e32 v62, v62, v33
	v_sub_f32_e32 v61, v61, v33
	v_sub_f32_e32 v60, v60, v33
	v_sub_f32_e32 v59, v59, v33
	v_sub_f32_e32 v58, v58, v33
	v_sub_f32_e32 v57, v57, v33
	v_sub_f32_e32 v56, v56, v33
	v_sub_f32_e32 v55, v55, v33
	v_sub_f32_e32 v54, v54, v33
	v_sub_f32_e32 v53, v53, v33
	v_sub_f32_e32 v52, v52, v33
	v_sub_f32_e32 v51, v51, v33
	v_sub_f32_e32 v50, v50, v33
	v_sub_f32_e32 v49, v49, v33
	v_sub_f32_e32 v48, v48, v33
	v_pk_mul_f32 v[14:15], v[14:15], v[34:35] op_sel_hi:[1,0]
	v_pk_mul_f32 v[12:13], v[12:13], v[34:35] op_sel_hi:[1,0]
	v_pk_mul_f32 v[10:11], v[10:11], v[34:35] op_sel_hi:[1,0]
	v_pk_mul_f32 v[8:9], v[8:9], v[34:35] op_sel_hi:[1,0]
	v_pk_mul_f32 v[6:7], v[6:7], v[34:35] op_sel_hi:[1,0]
	v_pk_mul_f32 v[4:5], v[4:5], v[34:35] op_sel_hi:[1,0]
	v_pk_mul_f32 v[2:3], v[2:3], v[34:35] op_sel_hi:[1,0]
	v_pk_mul_f32 v[0:1], v[0:1], v[34:35] op_sel_hi:[1,0]
	v_pk_mul_f32 v[30:31], v[30:31], v[34:35] op_sel_hi:[1,0]
	v_pk_mul_f32 v[28:29], v[28:29], v[34:35] op_sel_hi:[1,0]
	v_pk_mul_f32 v[26:27], v[26:27], v[34:35] op_sel_hi:[1,0]
	v_pk_mul_f32 v[24:25], v[24:25], v[34:35] op_sel_hi:[1,0]
	v_pk_mul_f32 v[22:23], v[22:23], v[34:35] op_sel_hi:[1,0]
	v_pk_mul_f32 v[20:21], v[20:21], v[34:35] op_sel_hi:[1,0]
	v_pk_mul_f32 v[18:19], v[18:19], v[34:35] op_sel_hi:[1,0]
	v_pk_mul_f32 v[16:17], v[16:17], v[34:35] op_sel_hi:[1,0]
	v_mov_b32_e32 v33, v32
	v_mov_b32_e32 v34, v32
	v_mov_b32_e32 v35, v32
	v_mov_b32_e32 v36, v32
	v_mov_b32_e32 v37, v32
	v_mov_b32_e32 v38, v32
	v_mov_b32_e32 v39, v32
	v_mov_b32_e32 v40, v32
	v_mov_b32_e32 v41, v32
	v_mov_b32_e32 v42, v32
	v_mov_b32_e32 v43, v32
	v_mov_b32_e32 v44, v32
	v_mov_b32_e32 v45, v32
	v_mov_b32_e32 v46, v32
	v_mov_b32_e32 v47, v32
	v_mov_b32_e32 v64, v32
	v_mov_b32_e32 v65, v32
	v_mov_b32_e32 v66, v32
	v_mov_b32_e32 v67, v32
	v_mov_b32_e32 v68, v32
	v_mov_b32_e32 v69, v32
	v_mov_b32_e32 v70, v32
	v_mov_b32_e32 v71, v32
	v_mov_b32_e32 v72, v32
	v_mov_b32_e32 v73, v32
	v_mov_b32_e32 v74, v32
	v_mov_b32_e32 v75, v32
	v_mov_b32_e32 v76, v32
	v_mov_b32_e32 v77, v32
	v_mov_b32_e32 v78, v32
	v_mov_b32_e32 v79, v32
	s_branch .LBB0_396

; template <int DV, int PAR, bool KW = true, bool KL = true, bool VL = true>
; __device__ __forceinline__ void attn_iter_full(AttnState<DV>& S, int t, LAS unsigned char* lds) {
;     constexpr int NDB = DV / 32, NS = 8 + 4 * NDB, NU = 27;
;     const LAS unsigned char* BK = lds + AT_K0 + (PAR ^ 1) * AT_KB + S.koff;
;     const LAS unsigned char* BV = lds + AT_V0 + PAR * AT_VB + S.voff;
;     f32x16& C0 = PAR ? S.sd0 : S.sc0; f32x16& C1 = PAR ? S.sd1 : S.sc1; f32x16& sn0 = PAR ? S.sc0 : S.sd0; f32x16& sn1 = PAR ? S.sc1 : S.sd1;
;     sn0 = S.negm; sn1 = S.negm;
;     u32x4 pw[4]; float mxa = 0.f, mxb = 0.f, mx = 0.f; f32x16 ssum;
;     constexpr int PD = (DV == 64) ? 3 : 2; bf16x8 fr[PD + 1];
;     ...
; #pragma unroll
;     for (int i = 0; i < PD; ++i) fr[i] = AT_FRAG(i);
;     __builtin_amdgcn_sched_barrier(0);
; #pragma unroll
;     for (int i = 0; i < NS; ++i) {
;         if (i + PD < NS) fr[(i + PD) % (PD + 1)] = AT_FRAG(i + PD);
;         if (i == 3) {
;             if (KW) *(LAS u32x4*)(lds + AT_K0 + PAR * AT_KB + S.kl) = S.kreg;
;             LAS unsigned char* W = lds + AT_V0 + (PAR ^ 1) * AT_VB + S.vl; *(LAS u32x4*)W = S.vreg0; if (DV == 128) *(LAS u32x4*)(W + 64 * 144) = S.vreg1; }
;         if (i == 5) { if (KL) S.kreg = *(const u32x4*)(S.kg + (size_t)(t + 3) * 4096);
;             if (VL) { S.vreg0 = *(const u32x4*)(S.vg + (t + 2) * 64); if (DV == 128) S.vreg1 = *(const u32x4*)(S.vg + (size_t)64 * TK + (t + 2) * 64); } }
;         if (i < 8) { if (i & 1) sn1 = MFMA32(fr[i % (PD + 1)], S.qr[i >> 1], sn1); else sn0 = MFMA32(fr[i % (PD + 1)], S.qr[i >> 1], sn0); }
;         else { const int j = i - 8; S.o[j % NDB] = MFMA32(fr[i % (PD + 1)], __builtin_bit_cast(bf16x8, pw[j / NDB]), S.o[j % NDB]); }
; #pragma unroll
;         for (int u = 0; u < NU; ++u) {
;             if (u * NS / NU != i) continue;
;             if (u < 20) {
;                 const int q = u / 5, r = u % 5;
;                 if (r < 4) { const int e = 8 * q + 2 * r;
;                     if (e < 16) { C0[e] = fast_exp2(C0[e]); C0[e + 1] = fast_exp2(C0[e + 1]); }
;                     else { C1[e - 16] = fast_exp2(C1[e - 16]); C1[e - 15] = fast_exp2(C1[e - 15]); } }
;                 else { if (q < 2) { const int b0 = 8 * q; pw[q].x = pk2(C0[b0], C0[b0 + 1]); pw[q].y = pk2(C0[b0 + 2], C0[b0 + 3]); pw[q].z = pk2(C0[b0 + 4], C0[b0 + 5]); pw[q].w = pk2(C0[b0 + 6], C0[b0 + 7]); }
.LBB0_414:
	ds_read_b128 v[64:67], v231 offset:9216
	ds_read_b128 v[68:71], v231 offset:13824
	s_waitcnt lgkmcnt(1)
	v_mfma_f32_32x32x16_bf16 v[144:159], v[64:67], v[174:177], v[96:111]
	ds_read_b128 v[72:75], v231 offset:9248
	v_exp_f32_e32 v64, v114
	v_exp_f32_e32 v66, v112
	v_exp_f32_e32 v67, v113
	v_exp_f32_e32 v65, v115
	s_waitcnt lgkmcnt(1)
	v_mfma_f32_32x32x16_bf16 v[128:143], v[68:71], v[174:177], v[96:111]
	ds_read_b128 v[76:79], v231 offset:13856
	v_exp_f32_e32 v68, v116
	v_exp_f32_e32 v69, v117
	s_waitcnt lgkmcnt(1)
	v_mfma_f32_32x32x16_bf16 v[144:159], v[72:75], v[170:173], v[144:159]
	ds_read_b128 v[112:115], v231 offset:9280
	v_exp_f32_e32 v70, v118
	v_exp_f32_e32 v71, v119
	s_waitcnt lgkmcnt(1)
	v_mfma_f32_32x32x16_bf16 v[128:143], v[76:79], v[170:173], v[128:143]
	ds_read_b128 v[116:119], v231 offset:13888
	s_waitcnt vmcnt(0)
	ds_write_b128 v232, v[178:181]
	ds_write_b128 v232, v[182:185] offset:36864
	ds_write_b128 v232, v[186:189] offset:46080
	v_cvt_pk_bf16_f32 v74, v66, v67
	v_cvt_pk_bf16_f32 v75, v64, v65
	v_cvt_pk_bf16_f32 v76, v68, v69
	v_cvt_pk_bf16_f32 v77, v70, v71
	s_waitcnt lgkmcnt(4)
	v_mfma_f32_32x32x16_bf16 v[144:159], v[112:115], v[166:169], v[144:159]
	ds_read_b128 v[234:237], v231 offset:9312
	v_exp_f32_e32 v72, v120
	v_exp_f32_e32 v73, v121
	ds_read_b128 v[112:115], v231 offset:13920
	global_load_dwordx4 v[178:181], v[206:207], off
	global_load_dwordx4 v[182:185], v[208:209], off offset:256
	v_lshl_add_u64 v[214:215], v[208:209], 0, s[16:17]
	global_load_dwordx4 v[186:189], v[214:215], off offset:256
	s_waitcnt lgkmcnt(5)
	v_mfma_f32_32x32x16_bf16 v[128:143], v[116:119], v[166:169], v[128:143]
	v_exp_f32_e32 v190, v122
	v_exp_f32_e32 v191, v123
	s_waitcnt lgkmcnt(1)
	v_mfma_f32_32x32x16_bf16 v[144:159], v[234:237], v[162:165], v[144:159]
	ds_read_b128 v[116:119], v230 offset:18432
	v_exp_f32_e32 v124, v124
	v_exp_f32_e32 v125, v125
	s_waitcnt lgkmcnt(1)
	v_mfma_f32_32x32x16_bf16 v[128:143], v[112:115], v[162:165], v[128:143]
	ds_read_b128 v[120:123], v230 offset:23040
	v_exp_f32_e32 v126, v126
	v_exp_f32_e32 v127, v127
	s_waitcnt lgkmcnt(1)
	v_mfma_f32_32x32x16_bf16 v[48:63], v[116:119], v[74:77], v[48:63]
	ds_read_b128 v[112:115], v230 offset:27648
	v_cvt_pk_bf16_f32 v116, v72, v73
	v_cvt_pk_bf16_f32 v117, v190, v191
	v_cvt_pk_bf16_f32 v118, v124, v125
	v_cvt_pk_bf16_f32 v119, v126, v127
	v_exp_f32_e32 v192, v80
	v_exp_f32_e32 v193, v81
	s_waitcnt lgkmcnt(1)
	v_mfma_f32_32x32x16_bf16 v[32:47], v[120:123], v[74:77], v[32:47]
	ds_read_b128 v[78:81], v230 offset:32256
	v_exp_f32_e32 v196, v82
	v_exp_f32_e32 v197, v83
	s_waitcnt lgkmcnt(1)
	v_mfma_f32_32x32x16_bf16 v[16:31], v[112:115], v[74:77], v[16:31]
	ds_read_b128 v[120:123], v230 offset:18464
	v_exp_f32_e32 v198, v84
	v_exp_f32_e32 v199, v85
	s_waitcnt lgkmcnt(1)
	v_mfma_f32_32x32x16_bf16 v[0:15], v[78:81], v[74:77], v[0:15]
	ds_read_b128 v[82:85], v230 offset:23072
	v_exp_f32_e32 v234, v86
	v_exp_f32_e32 v235, v87
	s_waitcnt lgkmcnt(1)
	v_mfma_f32_32x32x16_bf16 v[48:63], v[120:123], v[116:119], v[48:63]
	ds_read_b128 v[74:77], v230 offset:27680
	v_cvt_pk_bf16_f32 v78, v192, v193
	v_cvt_pk_bf16_f32 v79, v196, v197
	v_cvt_pk_bf16_f32 v80, v198, v199
	v_cvt_pk_bf16_f32 v81, v234, v235
	s_waitcnt lgkmcnt(1)
	v_mfma_f32_32x32x16_bf16 v[32:47], v[82:85], v[116:119], v[32:47]
	ds_read_b128 v[112:115], v230 offset:32288
	v_exp_f32_e32 v120, v88
	v_exp_f32_e32 v121, v89
	s_waitcnt lgkmcnt(1)
	v_mfma_f32_32x32x16_bf16 v[16:31], v[74:77], v[116:119], v[16:31]
	ds_read_b128 v[82:85], v230 offset:18496
	v_exp_f32_e32 v122, v90
	v_exp_f32_e32 v123, v91
	s_waitcnt lgkmcnt(1)
	v_mfma_f32_32x32x16_bf16 v[0:15], v[112:115], v[116:119], v[0:15]
	ds_read_b128 v[74:77], v230 offset:23104
	v_exp_f32_e32 v112, v92
	v_exp_f32_e32 v113, v93
	s_waitcnt lgkmcnt(1)
	v_mfma_f32_32x32x16_bf16 v[48:63], v[82:85], v[78:81], v[48:63]
	ds_read_b128 v[86:89], v230 offset:27712
	v_exp_f32_e32 v94, v94
	v_exp_f32_e32 v95, v95
	v_cvt_pk_bf16_f32 v82, v120, v121
	v_cvt_pk_bf16_f32 v83, v122, v123
	v_cvt_pk_bf16_f32 v84, v112, v113
	v_cvt_pk_bf16_f32 v85, v94, v95
	s_waitcnt lgkmcnt(1)
	v_mfma_f32_32x32x16_bf16 v[32:47], v[74:77], v[78:81], v[32:47]
	ds_read_b128 v[90:93], v230 offset:32320
	v_add_f32_e64 v74, v112, v124
	v_add_f32_e64 v75, v113, v125
	v_add_f32_e64 v76, v94, v126
	v_add_f32_e64 v77, v95, v127
	v_pk_add_f32 v[94:95], v[122:123], v[190:191]
	v_pk_add_f32 v[72:73], v[120:121], v[72:73]
	v_pk_add_f32 v[68:69], v[198:199], v[68:69]
	v_pk_add_f32 v[112:113], v[192:193], v[66:67]
	v_pk_add_f32 v[70:71], v[234:235], v[70:71]
	v_pk_add_f32 v[114:115], v[196:197], v[64:65]
	s_waitcnt lgkmcnt(1)
	v_mfma_f32_32x32x16_bf16 v[16:31], v[86:89], v[78:81], v[16:31]
	v_add_f32_e64 v70, v114, v70
	v_add_f32_e64 v71, v115, v71
	v_add_f32_e64 v68, v112, v68
	v_add_f32_e64 v69, v113, v69
	v_add_f32_e64 v70, v94, v70
	v_add_f32_e64 v71, v95, v71
	v_pk_add_f32 v[68:69], v[72:73], v[68:69]
	ds_read_b128 v[64:67], v230 offset:18528
	v_pk_add_f32 v[70:71], v[76:77], v[70:71]
	v_pk_add_f32 v[68:69], v[74:75], v[68:69]
	s_nop 0
	v_pk_mov_b32 v[72:73], v[68:69], v[70:71] op_sel:[1,0]
	v_mov_b32_e32 v69, v71
	v_pk_add_f32 v[68:69], v[72:73], v[68:69]
	s_nop 0
	v_add_f32_e32 v68, v68, v69
	v_add_f32_e32 v234, v216, v68
	s_waitcnt lgkmcnt(1)
	v_mfma_f32_32x32x16_bf16 v[0:15], v[90:93], v[78:81], v[0:15]
	ds_read_b128 v[68:71], v230 offset:23136
	v_max3_f32 v72, v144, v145, v128
	v_max3_f32 v76, v146, v147, v129
	v_max3_f32 v77, v72, v130, v131
	s_waitcnt lgkmcnt(1)
	v_mfma_f32_32x32x16_bf16 v[48:63], v[64:67], v[82:85], v[48:63]
	ds_read_b128 v[72:75], v230 offset:27744
	v_max3_f32 v64, v77, v148, v149
	v_max3_f32 v65, v76, v150, v151
	v_max3_f32 v76, v64, v132, v133
	v_max3_f32 v77, v65, v134, v135
	s_waitcnt lgkmcnt(1)
	v_mfma_f32_32x32x16_bf16 v[32:47], v[68:71], v[82:85], v[32:47]
	ds_read_b128 v[64:67], v230 offset:32352
	v_max3_f32 v68, v76, v152, v153
	v_max3_f32 v69, v77, v154, v155
	v_max3_f32 v68, v68, v136, v137
	v_max3_f32 v69, v69, v138, v139
	s_waitcnt lgkmcnt(1)
	v_mfma_f32_32x32x16_bf16 v[16:31], v[72:75], v[82:85], v[16:31]
	v_max3_f32 v68, v68, v156, v157
	v_max3_f32 v69, v69, v158, v159
	v_max3_f32 v68, v68, v140, v141
	v_max3_f32 v69, v69, v142, v143
	s_waitcnt lgkmcnt(0)
	v_mfma_f32_32x32x16_bf16 v[0:15], v[64:67], v[82:85], v[0:15]
	v_max_f32_e32 v64, v68, v69
	v_mov_b32_e32 v65, v64
	s_nop 1
	v_permlane32_swap_b32_e32 v64, v65
	v_max_f32_e32 v64, v64, v65
	s_nop 0
	v_cmp_lt_f32_e32 vcc, s3, v64
	s_cbranch_vccz .LBB0_416
; __device__ __forceinline__ float fast_exp2(float x) { return __builtin_amdgcn_exp2f(x); }
; template <int DV, int PAR, bool KW = true, bool KL = true, bool VL = true>
; __device__ __forceinline__ void attn_iter_full(AttnState<DV>& S, int t, LAS unsigned char* lds) {
;     ...
;     if (__any(mx > 8.0f)) {
;         const float dl = fmaxf(mx, 0.f), alpha = fast_exp2(-dl);
;         S.mrun += dl; S.lsum *= alpha;
; #pragma unroll
;         for (int i = 0; i < 16; ++i) { sn0[i] -= dl; sn1[i] -= dl; S.negm[i] = -S.mrun; }
; #pragma unroll
;         for (int d = 0; d < NDB; ++d)
; #pragma unroll
;             for (int i = 0; i < 16; ++i) S.o[d][i] *= alpha;
;     }
	v_max_f32_e32 v64, v64, v64
	v_max_f32_e32 v66, 0, v64
	v_exp_f32_e64 v68, -v66
	v_add_f32_e32 v233, v233, v66
	v_xor_b32_e32 v64, 0x80000000, v233
	v_pk_add_f32 v[144:145], v[144:145], v[66:67] op_sel_hi:[1,0] neg_lo:[0,1] neg_hi:[0,1]
	v_mul_f32_e32 v234, v234, v68
	v_pk_add_f32 v[128:129], v[128:129], v[66:67] op_sel_hi:[1,0] neg_lo:[0,1] neg_hi:[0,1]
	v_pk_add_f32 v[146:147], v[146:147], v[66:67] op_sel_hi:[1,0] neg_lo:[0,1] neg_hi:[0,1]
	v_pk_add_f32 v[130:131], v[130:131], v[66:67] op_sel_hi:[1,0] neg_lo:[0,1] neg_hi:[0,1]
	v_pk_add_f32 v[148:149], v[148:149], v[66:67] op_sel_hi:[1,0] neg_lo:[0,1] neg_hi:[0,1]
	v_pk_add_f32 v[132:133], v[132:133], v[66:67] op_sel_hi:[1,0] neg_lo:[0,1] neg_hi:[0,1]
	v_pk_add_f32 v[150:151], v[150:151], v[66:67] op_sel_hi:[1,0] neg_lo:[0,1] neg_hi:[0,1]
	v_pk_add_f32 v[134:135], v[134:135], v[66:67] op_sel_hi:[1,0] neg_lo:[0,1] neg_hi:[0,1]
	v_pk_add_f32 v[152:153], v[152:153], v[66:67] op_sel_hi:[1,0] neg_lo:[0,1] neg_hi:[0,1]
	v_pk_add_f32 v[136:137], v[136:137], v[66:67] op_sel_hi:[1,0] neg_lo:[0,1] neg_hi:[0,1]
	v_pk_add_f32 v[154:155], v[154:155], v[66:67] op_sel_hi:[1,0] neg_lo:[0,1] neg_hi:[0,1]
	v_pk_add_f32 v[138:139], v[138:139], v[66:67] op_sel_hi:[1,0] neg_lo:[0,1] neg_hi:[0,1]
	v_pk_add_f32 v[156:157], v[156:157], v[66:67] op_sel_hi:[1,0] neg_lo:[0,1] neg_hi:[0,1]
	v_pk_add_f32 v[140:141], v[140:141], v[66:67] op_sel_hi:[1,0] neg_lo:[0,1] neg_hi:[0,1]
	v_pk_add_f32 v[158:159], v[158:159], v[66:67] op_sel_hi:[1,0] neg_lo:[0,1] neg_hi:[0,1]
	v_pk_add_f32 v[142:143], v[142:143], v[66:67] op_sel_hi:[1,0] neg_lo:[0,1] neg_hi:[0,1]
	v_pk_mul_f32 v[62:63], v[62:63], v[68:69] op_sel_hi:[1,0]
	v_pk_mul_f32 v[60:61], v[60:61], v[68:69] op_sel_hi:[1,0]
	v_pk_mul_f32 v[58:59], v[58:59], v[68:69] op_sel_hi:[1,0]
	v_pk_mul_f32 v[56:57], v[56:57], v[68:69] op_sel_hi:[1,0]
	v_pk_mul_f32 v[54:55], v[54:55], v[68:69] op_sel_hi:[1,0]
	v_pk_mul_f32 v[52:53], v[52:53], v[68:69] op_sel_hi:[1,0]
	v_pk_mul_f32 v[50:51], v[50:51], v[68:69] op_sel_hi:[1,0]
	v_pk_mul_f32 v[48:49], v[48:49], v[68:69] op_sel_hi:[1,0]
	v_pk_mul_f32 v[46:47], v[46:47], v[68:69] op_sel_hi:[1,0]
	v_pk_mul_f32 v[44:45], v[44:45], v[68:69] op_sel_hi:[1,0]
	v_pk_mul_f32 v[42:43], v[42:43], v[68:69] op_sel_hi:[1,0]
	v_pk_mul_f32 v[40:41], v[40:41], v[68:69] op_sel_hi:[1,0]
	v_pk_mul_f32 v[38:39], v[38:39], v[68:69] op_sel_hi:[1,0]
	v_pk_mul_f32 v[36:37], v[36:37], v[68:69] op_sel_hi:[1,0]
	v_pk_mul_f32 v[34:35], v[34:35], v[68:69] op_sel_hi:[1,0]
	v_pk_mul_f32 v[32:33], v[32:33], v[68:69] op_sel_hi:[1,0]
	v_pk_mul_f32 v[30:31], v[30:31], v[68:69] op_sel_hi:[1,0]
	v_pk_mul_f32 v[28:29], v[28:29], v[68:69] op_sel_hi:[1,0]
	v_pk_mul_f32 v[26:27], v[26:27], v[68:69] op_sel_hi:[1,0]
	v_pk_mul_f32 v[24:25], v[24:25], v[68:69] op_sel_hi:[1,0]
	v_pk_mul_f32 v[22:23], v[22:23], v[68:69] op_sel_hi:[1,0]
	v_pk_mul_f32 v[20:21], v[20:21], v[68:69] op_sel_hi:[1,0]
	v_pk_mul_f32 v[18:19], v[18:19], v[68:69] op_sel_hi:[1,0]
	v_pk_mul_f32 v[16:17], v[16:17], v[68:69] op_sel_hi:[1,0]
	v_pk_mul_f32 v[14:15], v[14:15], v[68:69] op_sel_hi:[1,0]
	v_pk_mul_f32 v[12:13], v[12:13], v[68:69] op_sel_hi:[1,0]
	v_pk_mul_f32 v[10:11], v[10:11], v[68:69] op_sel_hi:[1,0]
	v_pk_mul_f32 v[8:9], v[8:9], v[68:69] op_sel_hi:[1,0]
	v_pk_mul_f32 v[6:7], v[6:7], v[68:69] op_sel_hi:[1,0]
	v_pk_mul_f32 v[4:5], v[4:5], v[68:69] op_sel_hi:[1,0]
	v_pk_mul_f32 v[2:3], v[2:3], v[68:69] op_sel_hi:[1,0]
	v_pk_mul_f32 v[0:1], v[0:1], v[68:69] op_sel_hi:[1,0]
	v_mov_b32_e32 v65, v64
	v_mov_b32_e32 v66, v64
	v_mov_b32_e32 v67, v64
	v_mov_b32_e32 v68, v64
	v_mov_b32_e32 v69, v64
	v_mov_b32_e32 v70, v64
	v_mov_b32_e32 v71, v64
	v_mov_b32_e32 v72, v64
	v_mov_b32_e32 v73, v64
	v_mov_b32_e32 v74, v64
	v_mov_b32_e32 v75, v64
	v_mov_b32_e32 v76, v64
	v_mov_b32_e32 v77, v64
	v_mov_b32_e32 v78, v64
	v_mov_b32_e32 v79, v64
	v_mov_b32_e32 v96, v64
	v_mov_b32_e32 v97, v64
	v_mov_b32_e32 v98, v64
	v_mov_b32_e32 v99, v64
	v_mov_b32_e32 v100, v64
	v_mov_b32_e32 v101, v64
	v_mov_b32_e32 v102, v64
	v_mov_b32_e32 v103, v64
	v_mov_b32_e32 v104, v64
	v_mov_b32_e32 v105, v64
	v_mov_b32_e32 v106, v64
	v_mov_b32_e32 v107, v64
	v_mov_b32_e32 v108, v64
	v_mov_b32_e32 v109, v64
	v_mov_b32_e32 v110, v64
	v_mov_b32_e32 v111, v64
	s_branch .LBB0_417
; template <int DV, int PAR, bool KW = true, bool KL = true, bool VL = true>
; __device__ __forceinline__ void attn_iter_full(AttnState<DV>& S, int t, LAS unsigned char* lds) {
;     constexpr int NDB = DV / 32, NS = 8 + 4 * NDB, NU = 27;
;     const LAS unsigned char* BK = lds + AT_K0 + (PAR ^ 1) * AT_KB + S.koff;
;     const LAS unsigned char* BV = lds + AT_V0 + PAR * AT_VB + S.voff;
;     f32x16& C0 = PAR ? S.sd0 : S.sc0; f32x16& C1 = PAR ? S.sd1 : S.sc1; f32x16& sn0 = PAR ? S.sc0 : S.sd0; f32x16& sn1 = PAR ? S.sc1 : S.sd1;
;     sn0 = S.negm; sn1 = S.negm;
;     u32x4 pw[4]; float mxa = 0.f, mxb = 0.f, mx = 0.f; f32x16 ssum;
;     constexpr int PD = (DV == 64) ? 3 : 2; bf16x8 fr[PD + 1];
;     ...
; #pragma unroll
;     for (int i = 0; i < PD; ++i) fr[i] = AT_FRAG(i);
;     __builtin_amdgcn_sched_barrier(0);
; #pragma unroll
;     for (int i = 0; i < NS; ++i) {
;         if (i + PD < NS) fr[(i + PD) % (PD + 1)] = AT_FRAG(i + PD);
;         if (i == 3) {
;             if (KW) *(LAS u32x4*)(lds + AT_K0 + PAR * AT_KB + S.kl) = S.kreg;
;             LAS unsigned char* W = lds + AT_V0 + (PAR ^ 1) * AT_VB + S.vl; *(LAS u32x4*)W = S.vreg0; if (DV == 128) *(LAS u32x4*)(W + 64 * 144) = S.vreg1; }
;         if (i == 5) { if (KL) S.kreg = *(const u32x4*)(S.kg + (size_t)(t + 3) * 4096);
;             if (VL) { S.vreg0 = *(const u32x4*)(S.vg + (t + 2) * 64); if (DV == 128) S.vreg1 = *(const u32x4*)(S.vg + (size_t)64 * TK + (t + 2) * 64); } }
;         if (i < 8) { if (i & 1) sn1 = MFMA32(fr[i % (PD + 1)], S.qr[i >> 1], sn1); else sn0 = MFMA32(fr[i % (PD + 1)], S.qr[i >> 1], sn0); }
;         else { const int j = i - 8; S.o[j % NDB] = MFMA32(fr[i % (PD + 1)], __builtin_bit_cast(bf16x8, pw[j / NDB]), S.o[j % NDB]); }
; #pragma unroll
;         for (int u = 0; u < NU; ++u) {
;             if (u * NS / NU != i) continue;
;             if (u < 20) {
;                 const int q = u / 5, r = u % 5;
;                 if (r < 4) { const int e = 8 * q + 2 * r;
;                     if (e < 16) { C0[e] = fast_exp2(C0[e]); C0[e + 1] = fast_exp2(C0[e + 1]); }
;                     else { C1[e - 16] = fast_exp2(C1[e - 16]); C1[e - 15] = fast_exp2(C1[e - 15]); } }
;                 else { if (q < 2) { const int b0 = 8 * q; pw[q].x = pk2(C0[b0], C0[b0 + 1]); pw[q].y = pk2(C0[b0 + 2], C0[b0 + 3]); pw[q].z = pk2(C0[b0 + 4], C0[b0 + 5]); pw[q].w = pk2(C0[b0 + 6], C0[b0 + 7]); }
.LBB0_416:
.LBB0_417:
	s_barrier
	ds_read_b128 v[80:83], v231
	ds_read_b128 v[242:245], v231 offset:4608
	s_waitcnt lgkmcnt(1)
	v_mfma_f32_32x32x16_bf16 v[112:127], v[80:83], v[174:177], v[96:111]
	ds_read_b128 v[246:249], v231 offset:32
	v_exp_f32_e32 v216, v144
	v_exp_f32_e32 v217, v145
	v_exp_f32_e32 v144, v146
	v_exp_f32_e32 v145, v147
	s_waitcnt lgkmcnt(1)
	v_mfma_f32_32x32x16_bf16 v[80:95], v[242:245], v[174:177], v[96:111]
	ds_read_b128 v[190:193], v231 offset:4640
	v_exp_f32_e32 v146, v148
	v_exp_f32_e32 v147, v149
	s_waitcnt lgkmcnt(1)
	v_mfma_f32_32x32x16_bf16 v[112:127], v[246:249], v[170:173], v[112:127]
	ds_read_b128 v[242:245], v231 offset:64
	v_exp_f32_e32 v148, v150
	v_exp_f32_e32 v149, v151
	s_waitcnt lgkmcnt(1)
	v_mfma_f32_32x32x16_bf16 v[80:95], v[190:193], v[170:173], v[80:95]
	ds_read_b128 v[246:249], v231 offset:4672
	s_waitcnt vmcnt(0)
	ds_write_b128 v232, v[178:181] offset:9216
	ds_write_b128 v232, v[182:185] offset:18432
	ds_write_b128 v232, v[186:189] offset:27648
	v_cvt_pk_bf16_f32 v196, v216, v217
	v_cvt_pk_bf16_f32 v197, v144, v145
	v_cvt_pk_bf16_f32 v198, v146, v147
	v_cvt_pk_bf16_f32 v199, v148, v149
	s_waitcnt lgkmcnt(4)
	v_mfma_f32_32x32x16_bf16 v[112:127], v[242:245], v[166:169], v[112:127]
	ds_read_b128 v[190:193], v231 offset:96
	v_exp_f32_e32 v150, v152
	v_exp_f32_e32 v151, v153
	v_lshl_add_u64 v[152:153], v[206:207], 0, s[100:101]
	ds_read_b128 v[242:245], v231 offset:4704
	global_load_dwordx4 v[178:181], v[152:153], off
	global_load_dwordx4 v[182:185], v[208:209], off offset:384
	global_load_dwordx4 v[186:189], v[214:215], off offset:384
	s_waitcnt lgkmcnt(5)
	v_mfma_f32_32x32x16_bf16 v[80:95], v[246:249], v[166:169], v[80:95]
	v_exp_f32_e32 v214, v154
	v_exp_f32_e32 v215, v155
	s_waitcnt lgkmcnt(1)
	v_mfma_f32_32x32x16_bf16 v[112:127], v[190:193], v[162:165], v[112:127]
	ds_read_b128 v[152:155], v230 offset:36864
	v_exp_f32_e32 v236, v156
	v_exp_f32_e32 v237, v157
	s_waitcnt lgkmcnt(1)
	v_mfma_f32_32x32x16_bf16 v[80:95], v[242:245], v[162:165], v[80:95]
	ds_read_b128 v[190:193], v230 offset:41472
	v_exp_f32_e32 v242, v158
	v_exp_f32_e32 v243, v159
	s_waitcnt lgkmcnt(1)
	v_mfma_f32_32x32x16_bf16 v[48:63], v[152:155], v[196:199], v[48:63]
	ds_read_b128 v[156:159], v230 offset:46080
	v_cvt_pk_bf16_f32 v152, v150, v151
	v_cvt_pk_bf16_f32 v153, v214, v215
	v_cvt_pk_bf16_f32 v154, v236, v237
	v_cvt_pk_bf16_f32 v155, v242, v243
	v_exp_f32_e32 v244, v128
	v_exp_f32_e32 v245, v129
	s_waitcnt lgkmcnt(1)
	v_mfma_f32_32x32x16_bf16 v[32:47], v[190:193], v[196:199], v[32:47]
	ds_read_b128 v[210:213], v230 offset:50688
	v_exp_f32_e32 v246, v130
	v_exp_f32_e32 v247, v131
	s_waitcnt lgkmcnt(1)
	v_mfma_f32_32x32x16_bf16 v[16:31], v[156:159], v[196:199], v[16:31]
	ds_read_b128 v[128:131], v230 offset:36896
	v_exp_f32_e32 v248, v132
	v_exp_f32_e32 v249, v133
	s_waitcnt lgkmcnt(1)
	v_mfma_f32_32x32x16_bf16 v[0:15], v[210:213], v[196:199], v[0:15]
	ds_read_b128 v[156:159], v230 offset:41504
	v_exp_f32_e32 v196, v134
	v_exp_f32_e32 v197, v135
	s_waitcnt lgkmcnt(1)
	v_mfma_f32_32x32x16_bf16 v[48:63], v[128:131], v[152:155], v[48:63]
	ds_read_b128 v[132:135], v230 offset:46112
	v_cvt_pk_bf16_f32 v128, v244, v245
	v_cvt_pk_bf16_f32 v129, v246, v247
	v_cvt_pk_bf16_f32 v130, v248, v249
	v_cvt_pk_bf16_f32 v131, v196, v197
	s_waitcnt lgkmcnt(1)
	v_mfma_f32_32x32x16_bf16 v[32:47], v[156:159], v[152:155], v[32:47]
	ds_read_b128 v[190:193], v230 offset:50720
	v_exp_f32_e32 v198, v136
	v_exp_f32_e32 v199, v137
	s_waitcnt lgkmcnt(1)
	v_mfma_f32_32x32x16_bf16 v[16:31], v[132:135], v[152:155], v[16:31]
	ds_read_b128 v[156:159], v230 offset:36928
	v_exp_f32_e32 v210, v138
	v_exp_f32_e32 v211, v139
	s_waitcnt lgkmcnt(1)
	v_mfma_f32_32x32x16_bf16 v[0:15], v[190:193], v[152:155], v[0:15]
	ds_read_b128 v[132:135], v230 offset:41536
	v_exp_f32_e32 v190, v140
	v_exp_f32_e32 v191, v141
	s_waitcnt lgkmcnt(1)
	v_mfma_f32_32x32x16_bf16 v[48:63], v[156:159], v[128:131], v[48:63]
	ds_read_b128 v[136:139], v230 offset:46144
	v_exp_f32_e32 v156, v142
	v_exp_f32_e32 v157, v143
	v_cvt_pk_bf16_f32 v140, v198, v199
	v_cvt_pk_bf16_f32 v141, v210, v211
	v_cvt_pk_bf16_f32 v142, v190, v191
	v_cvt_pk_bf16_f32 v143, v156, v157
	s_waitcnt lgkmcnt(1)
	v_mfma_f32_32x32x16_bf16 v[32:47], v[132:135], v[128:131], v[32:47]
	ds_read_b128 v[152:155], v230 offset:50752
	v_add_f32_e64 v158, v190, v236
	v_add_f32_e64 v159, v191, v237
	v_add_f32_e64 v156, v156, v242
	v_add_f32_e64 v157, v157, v243
	v_pk_add_f32 v[190:191], v[210:211], v[214:215]
	v_pk_add_f32 v[150:151], v[198:199], v[150:151]
	v_pk_add_f32 v[146:147], v[248:249], v[146:147]
	v_pk_add_f32 v[192:193], v[244:245], v[216:217]
	v_pk_add_f32 v[148:149], v[196:197], v[148:149]
	v_pk_add_f32 v[144:145], v[246:247], v[144:145]
	s_waitcnt lgkmcnt(1)
	v_mfma_f32_32x32x16_bf16 v[16:31], v[136:139], v[128:131], v[16:31]
	v_add_f32_e64 v136, v144, v148
	v_add_f32_e64 v137, v145, v149
	v_add_f32_e64 v138, v192, v146
	v_add_f32_e64 v139, v193, v147
	v_add_f32_e64 v136, v190, v136
	v_add_f32_e64 v137, v191, v137
	v_pk_add_f32 v[138:139], v[150:151], v[138:139]
	v_pk_add_f32 v[136:137], v[156:157], v[136:137]
	v_pk_add_f32 v[138:139], v[158:159], v[138:139]
	ds_read_b128 v[132:135], v230 offset:36960
	v_pk_mov_b32 v[144:145], v[138:139], v[136:137] op_sel:[1,0]
	v_mov_b32_e32 v139, v137
	v_pk_add_f32 v[136:137], v[144:145], v[138:139]
	s_nop 0
	v_add_f32_e32 v136, v136, v137
	v_add_f32_e32 v216, v234, v136
	s_waitcnt lgkmcnt(1)
	v_mfma_f32_32x32x16_bf16 v[0:15], v[152:155], v[128:131], v[0:15]
	ds_read_b128 v[136:139], v230 offset:41568
	v_max3_f32 v128, v112, v113, v80
	v_max3_f32 v144, v114, v115, v81
	v_max3_f32 v145, v128, v82, v83
	s_waitcnt lgkmcnt(1)
	v_mfma_f32_32x32x16_bf16 v[48:63], v[132:135], v[140:143], v[48:63]
	ds_read_b128 v[128:131], v230 offset:46176
	v_max3_f32 v132, v145, v116, v117
	v_max3_f32 v133, v144, v118, v119
	v_max3_f32 v144, v132, v84, v85
	v_max3_f32 v145, v133, v86, v87
	s_waitcnt lgkmcnt(1)
	v_mfma_f32_32x32x16_bf16 v[32:47], v[136:139], v[140:143], v[32:47]
	ds_read_b128 v[132:135], v230 offset:50784
	v_max3_f32 v136, v144, v120, v121
	v_max3_f32 v137, v145, v122, v123
	v_max3_f32 v136, v136, v88, v89
	v_max3_f32 v137, v137, v90, v91
	s_waitcnt lgkmcnt(1)
	v_mfma_f32_32x32x16_bf16 v[16:31], v[128:131], v[140:143], v[16:31]
	v_max3_f32 v128, v136, v124, v125
	v_max3_f32 v129, v137, v126, v127
	v_max3_f32 v128, v128, v92, v93
	v_max3_f32 v129, v129, v94, v95
	s_waitcnt lgkmcnt(0)
	v_mfma_f32_32x32x16_bf16 v[0:15], v[132:135], v[140:143], v[0:15]
	v_max_f32_e32 v128, v128, v129
	v_mov_b32_e32 v129, v128
	s_nop 1
	v_permlane32_swap_b32_e32 v128, v129
	v_max_f32_e32 v128, v128, v129
	s_nop 0
	v_cmp_lt_f32_e32 vcc, s3, v128
	s_cbranch_vccz .LBB0_413
; __device__ __forceinline__ float fast_exp2(float x) { return __builtin_amdgcn_exp2f(x); }
; template <int DV, int PAR, bool KW = true, bool KL = true, bool VL = true>
; __device__ __forceinline__ void attn_iter_full(AttnState<DV>& S, int t, LAS unsigned char* lds) {
;     ...
;     if (__any(mx > 8.0f)) {
;         const float dl = fmaxf(mx, 0.f), alpha = fast_exp2(-dl);
;         S.mrun += dl; S.lsum *= alpha;
; #pragma unroll
;         for (int i = 0; i < 16; ++i) { sn0[i] -= dl; sn1[i] -= dl; S.negm[i] = -S.mrun; }
; #pragma unroll
;         for (int d = 0; d < NDB; ++d)
; #pragma unroll
;             for (int i = 0; i < 16; ++i) S.o[d][i] *= alpha;
;     }
	v_max_f32_e32 v64, v128, v128
	v_max_f32_e32 v65, 0, v64
	v_exp_f32_e64 v66, -v65
	v_add_f32_e32 v233, v233, v65
	v_xor_b32_e32 v64, 0x80000000, v233
	v_sub_f32_e32 v127, v127, v65
	v_mul_f32_e32 v216, v216, v66
	v_sub_f32_e32 v126, v126, v65
	v_sub_f32_e32 v125, v125, v65
	v_sub_f32_e32 v124, v124, v65
	v_sub_f32_e32 v123, v123, v65
	v_sub_f32_e32 v122, v122, v65
	v_sub_f32_e32 v121, v121, v65
	v_sub_f32_e32 v120, v120, v65
	v_sub_f32_e32 v119, v119, v65
	v_sub_f32_e32 v118, v118, v65
	v_sub_f32_e32 v117, v117, v65
	v_sub_f32_e32 v116, v116, v65
	v_sub_f32_e32 v115, v115, v65
	v_sub_f32_e32 v114, v114, v65
	v_sub_f32_e32 v113, v113, v65
	v_sub_f32_e32 v112, v112, v65
	v_sub_f32_e32 v95, v95, v65
	v_sub_f32_e32 v94, v94, v65
	v_sub_f32_e32 v93, v93, v65
	v_sub_f32_e32 v92, v92, v65
	v_sub_f32_e32 v91, v91, v65
	v_sub_f32_e32 v90, v90, v65
	v_sub_f32_e32 v89, v89, v65
	v_sub_f32_e32 v88, v88, v65
	v_sub_f32_e32 v87, v87, v65
	v_sub_f32_e32 v86, v86, v65
	v_sub_f32_e32 v85, v85, v65
	v_sub_f32_e32 v84, v84, v65
	v_sub_f32_e32 v83, v83, v65
	v_sub_f32_e32 v82, v82, v65
	v_sub_f32_e32 v81, v81, v65
	v_sub_f32_e32 v80, v80, v65
	v_pk_mul_f32 v[62:63], v[62:63], v[66:67] op_sel_hi:[1,0]
	v_pk_mul_f32 v[60:61], v[60:61], v[66:67] op_sel_hi:[1,0]
	v_pk_mul_f32 v[58:59], v[58:59], v[66:67] op_sel_hi:[1,0]
	v_pk_mul_f32 v[56:57], v[56:57], v[66:67] op_sel_hi:[1,0]
	v_pk_mul_f32 v[54:55], v[54:55], v[66:67] op_sel_hi:[1,0]
	v_pk_mul_f32 v[52:53], v[52:53], v[66:67] op_sel_hi:[1,0]
	v_pk_mul_f32 v[50:51], v[50:51], v[66:67] op_sel_hi:[1,0]
	v_pk_mul_f32 v[48:49], v[48:49], v[66:67] op_sel_hi:[1,0]
	v_pk_mul_f32 v[46:47], v[46:47], v[66:67] op_sel_hi:[1,0]
	v_pk_mul_f32 v[44:45], v[44:45], v[66:67] op_sel_hi:[1,0]
	v_pk_mul_f32 v[42:43], v[42:43], v[66:67] op_sel_hi:[1,0]
	v_pk_mul_f32 v[40:41], v[40:41], v[66:67] op_sel_hi:[1,0]
	v_pk_mul_f32 v[38:39], v[38:39], v[66:67] op_sel_hi:[1,0]
	v_pk_mul_f32 v[36:37], v[36:37], v[66:67] op_sel_hi:[1,0]
	v_pk_mul_f32 v[34:35], v[34:35], v[66:67] op_sel_hi:[1,0]
	v_pk_mul_f32 v[32:33], v[32:33], v[66:67] op_sel_hi:[1,0]
	v_pk_mul_f32 v[30:31], v[30:31], v[66:67] op_sel_hi:[1,0]
	v_pk_mul_f32 v[28:29], v[28:29], v[66:67] op_sel_hi:[1,0]
	v_pk_mul_f32 v[26:27], v[26:27], v[66:67] op_sel_hi:[1,0]
	v_pk_mul_f32 v[24:25], v[24:25], v[66:67] op_sel_hi:[1,0]
	v_pk_mul_f32 v[22:23], v[22:23], v[66:67] op_sel_hi:[1,0]
	v_pk_mul_f32 v[20:21], v[20:21], v[66:67] op_sel_hi:[1,0]
	v_pk_mul_f32 v[18:19], v[18:19], v[66:67] op_sel_hi:[1,0]
	v_pk_mul_f32 v[16:17], v[16:17], v[66:67] op_sel_hi:[1,0]
	v_pk_mul_f32 v[14:15], v[14:15], v[66:67] op_sel_hi:[1,0]
	v_pk_mul_f32 v[12:13], v[12:13], v[66:67] op_sel_hi:[1,0]
	v_pk_mul_f32 v[10:11], v[10:11], v[66:67] op_sel_hi:[1,0]
	v_pk_mul_f32 v[8:9], v[8:9], v[66:67] op_sel_hi:[1,0]
	v_pk_mul_f32 v[6:7], v[6:7], v[66:67] op_sel_hi:[1,0]
	v_pk_mul_f32 v[4:5], v[4:5], v[66:67] op_sel_hi:[1,0]
	v_pk_mul_f32 v[2:3], v[2:3], v[66:67] op_sel_hi:[1,0]
	v_pk_mul_f32 v[0:1], v[0:1], v[66:67] op_sel_hi:[1,0]
	v_mov_b32_e32 v65, v64
	v_mov_b32_e32 v66, v64
	v_mov_b32_e32 v67, v64
	v_mov_b32_e32 v68, v64
	v_mov_b32_e32 v69, v64
	v_mov_b32_e32 v70, v64
	v_mov_b32_e32 v71, v64
	v_mov_b32_e32 v72, v64
	v_mov_b32_e32 v73, v64
	v_mov_b32_e32 v74, v64
	v_mov_b32_e32 v75, v64
	v_mov_b32_e32 v76, v64
	v_mov_b32_e32 v77, v64
	v_mov_b32_e32 v78, v64
	v_mov_b32_e32 v79, v64
	v_mov_b32_e32 v96, v64
	v_mov_b32_e32 v97, v64
	v_mov_b32_e32 v98, v64
	v_mov_b32_e32 v99, v64
	v_mov_b32_e32 v100, v64
	v_mov_b32_e32 v101, v64
	v_mov_b32_e32 v102, v64
	v_mov_b32_e32 v103, v64
	v_mov_b32_e32 v104, v64
	v_mov_b32_e32 v105, v64
	v_mov_b32_e32 v106, v64
	v_mov_b32_e32 v107, v64
	v_mov_b32_e32 v108, v64
	v_mov_b32_e32 v109, v64
	v_mov_b32_e32 v110, v64
	v_mov_b32_e32 v111, v64
	s_branch .LBB0_413

; template <int DV, int PAR, bool KW = true, bool KL = true, bool VL = true>
; __device__ __forceinline__ void attn_iter_full(AttnState<DV>& S, int t, LAS unsigned char* lds) {
;     constexpr int NDB = DV / 32, NS = 8 + 4 * NDB, NU = 27;
;     const LAS unsigned char* BK = lds + AT_K0 + (PAR ^ 1) * AT_KB + S.koff;
;     const LAS unsigned char* BV = lds + AT_V0 + PAR * AT_VB + S.voff;
;     f32x16& C0 = PAR ? S.sd0 : S.sc0; f32x16& C1 = PAR ? S.sd1 : S.sc1; f32x16& sn0 = PAR ? S.sc0 : S.sd0; f32x16& sn1 = PAR ? S.sc1 : S.sd1;
;     sn0 = S.negm; sn1 = S.negm;
;     u32x4 pw[4]; float mxa = 0.f, mxb = 0.f, mx = 0.f; f32x16 ssum;
;     constexpr int PD = (DV == 64) ? 3 : 2; bf16x8 fr[PD + 1];
;     ...
; #pragma unroll
;     for (int i = 0; i < PD; ++i) fr[i] = AT_FRAG(i);
;     __builtin_amdgcn_sched_barrier(0);
; #pragma unroll
;     for (int i = 0; i < NS; ++i) {
;         if (i + PD < NS) fr[(i + PD) % (PD + 1)] = AT_FRAG(i + PD);
;         if (i == 3) {
;             if (KW) *(LAS u32x4*)(lds + AT_K0 + PAR * AT_KB + S.kl) = S.kreg;
;             LAS unsigned char* W = lds + AT_V0 + (PAR ^ 1) * AT_VB + S.vl; *(LAS u32x4*)W = S.vreg0; if (DV == 128) *(LAS u32x4*)(W + 64 * 144) = S.vreg1; }
;         if (i == 5) { if (KL) S.kreg = *(const u32x4*)(S.kg + (size_t)(t + 3) * 4096);
;             if (VL) { S.vreg0 = *(const u32x4*)(S.vg + (t + 2) * 64); if (DV == 128) S.vreg1 = *(const u32x4*)(S.vg + (size_t)64 * TK + (t + 2) * 64); } }
;         if (i < 8) { if (i & 1) sn1 = MFMA32(fr[i % (PD + 1)], S.qr[i >> 1], sn1); else sn0 = MFMA32(fr[i % (PD + 1)], S.qr[i >> 1], sn0); }
;         else { const int j = i - 8; S.o[j % NDB] = MFMA32(fr[i % (PD + 1)], __builtin_bit_cast(bf16x8, pw[j / NDB]), S.o[j % NDB]); }
; #pragma unroll
;         for (int u = 0; u < NU; ++u) {
;             if (u * NS / NU != i) continue;
;             if (u < 20) {
;                 const int q = u / 5, r = u % 5;
;                 if (r < 4) { const int e = 8 * q + 2 * r;
;                     if (e < 16) { C0[e] = fast_exp2(C0[e]); C0[e + 1] = fast_exp2(C0[e + 1]); }
;                     else { C1[e - 16] = fast_exp2(C1[e - 16]); C1[e - 15] = fast_exp2(C1[e - 15]); } }
;                 else { if (q < 2) { const int b0 = 8 * q; pw[q].x = pk2(C0[b0], C0[b0 + 1]); pw[q].y = pk2(C0[b0 + 2], C0[b0 + 3]); pw[q].z = pk2(C0[b0 + 4], C0[b0 + 5]); pw[q].w = pk2(C0[b0 + 6], C0[b0 + 7]); }
.LBB0_429:
.LBB0_430:
	s_barrier
	ds_read_b128 v[80:83], v234
	ds_read_b128 v[190:193], v234 offset:4608
	s_waitcnt lgkmcnt(1)
	v_mfma_f32_32x32x16_bf16 v[112:127], v[80:83], v[174:177], v[96:111]
	ds_read_b128 v[196:199], v234 offset:32
	v_exp_f32_e32 v216, v144
	v_exp_f32_e32 v217, v145
	v_exp_f32_e32 v144, v146
	v_exp_f32_e32 v145, v147
	s_waitcnt lgkmcnt(1)
	v_mfma_f32_32x32x16_bf16 v[80:95], v[190:193], v[174:177], v[96:111]
	ds_read_b128 v[242:245], v234 offset:4640
	v_exp_f32_e32 v146, v148
	v_exp_f32_e32 v147, v149
	s_waitcnt lgkmcnt(1)
	v_mfma_f32_32x32x16_bf16 v[112:127], v[196:199], v[170:173], v[112:127]
	ds_read_b128 v[190:193], v234 offset:64
	v_exp_f32_e32 v148, v150
	v_exp_f32_e32 v149, v151
	s_waitcnt lgkmcnt(1)
	v_mfma_f32_32x32x16_bf16 v[80:95], v[242:245], v[170:173], v[80:95]
	ds_read_b128 v[196:199], v234 offset:4672
	s_waitcnt vmcnt(0)
	ds_write_b128 v235, v[178:181] offset:9216
	ds_write_b128 v235, v[182:185] offset:18432
	ds_write_b128 v235, v[186:189] offset:27648
	v_cvt_pk_bf16_f32 v246, v216, v217
	v_cvt_pk_bf16_f32 v247, v144, v145
	v_cvt_pk_bf16_f32 v248, v146, v147
	v_cvt_pk_bf16_f32 v249, v148, v149
	s_waitcnt lgkmcnt(4)
	v_mfma_f32_32x32x16_bf16 v[112:127], v[190:193], v[166:169], v[112:127]
	ds_read_b128 v[242:245], v234 offset:96
	v_exp_f32_e32 v150, v152
	v_exp_f32_e32 v151, v153
	v_lshl_add_u64 v[152:153], v[206:207], 0, s[100:101]
	ds_read_b128 v[190:193], v234 offset:4704
	global_load_dwordx4 v[186:189], v[152:153], off
	global_load_dwordx4 v[178:181], v[208:209], off offset:384
	global_load_dwordx4 v[182:185], v[214:215], off offset:384
	s_waitcnt lgkmcnt(5)
	v_mfma_f32_32x32x16_bf16 v[80:95], v[196:199], v[166:169], v[80:95]
	v_exp_f32_e32 v210, v154
	v_exp_f32_e32 v211, v155
	s_waitcnt lgkmcnt(1)
	v_mfma_f32_32x32x16_bf16 v[112:127], v[242:245], v[162:165], v[112:127]
	ds_read_b128 v[152:155], v233 offset:36864
	v_exp_f32_e32 v212, v156
	v_exp_f32_e32 v213, v157
	s_waitcnt lgkmcnt(1)
	v_mfma_f32_32x32x16_bf16 v[80:95], v[190:193], v[162:165], v[80:95]
	ds_read_b128 v[196:199], v233 offset:41472
	v_exp_f32_e32 v214, v158
	v_exp_f32_e32 v215, v159
	s_waitcnt lgkmcnt(1)
	v_mfma_f32_32x32x16_bf16 v[0:15], v[152:155], v[246:249], v[0:15]
	ds_read_b128 v[156:159], v233 offset:46080
	v_cvt_pk_bf16_f32 v152, v150, v151
	v_cvt_pk_bf16_f32 v153, v210, v211
	v_cvt_pk_bf16_f32 v154, v212, v213
	v_cvt_pk_bf16_f32 v155, v214, v215
	v_exp_f32_e32 v242, v128
	v_exp_f32_e32 v243, v129
	s_waitcnt lgkmcnt(1)
	v_mfma_f32_32x32x16_bf16 v[48:63], v[196:199], v[246:249], v[48:63]
	ds_read_b128 v[190:193], v233 offset:50688
	v_exp_f32_e32 v196, v130
	v_exp_f32_e32 v197, v131
	s_waitcnt lgkmcnt(1)
	v_mfma_f32_32x32x16_bf16 v[32:47], v[156:159], v[246:249], v[32:47]
	ds_read_b128 v[128:131], v233 offset:36896
	v_exp_f32_e32 v198, v132
	v_exp_f32_e32 v199, v133
	s_waitcnt lgkmcnt(1)
	v_mfma_f32_32x32x16_bf16 v[16:31], v[190:193], v[246:249], v[16:31]
	ds_read_b128 v[156:159], v233 offset:41504
	v_exp_f32_e32 v244, v134
	v_exp_f32_e32 v245, v135
	s_waitcnt lgkmcnt(1)
	v_mfma_f32_32x32x16_bf16 v[0:15], v[128:131], v[152:155], v[0:15]
	ds_read_b128 v[132:135], v233 offset:46112
	v_cvt_pk_bf16_f32 v128, v242, v243
	v_cvt_pk_bf16_f32 v129, v196, v197
	v_cvt_pk_bf16_f32 v130, v198, v199
	v_cvt_pk_bf16_f32 v131, v244, v245
	s_waitcnt lgkmcnt(1)
	v_mfma_f32_32x32x16_bf16 v[48:63], v[156:159], v[152:155], v[48:63]
	ds_read_b128 v[190:193], v233 offset:50720
	v_exp_f32_e32 v246, v136
	v_exp_f32_e32 v247, v137
	s_waitcnt lgkmcnt(1)
	v_mfma_f32_32x32x16_bf16 v[32:47], v[132:135], v[152:155], v[32:47]
	ds_read_b128 v[156:159], v233 offset:36928
	v_exp_f32_e32 v248, v138
	v_exp_f32_e32 v249, v139
	s_waitcnt lgkmcnt(1)
	v_mfma_f32_32x32x16_bf16 v[16:31], v[190:193], v[152:155], v[16:31]
	ds_read_b128 v[132:135], v233 offset:41536
	v_exp_f32_e32 v190, v140
	v_exp_f32_e32 v191, v141
	s_waitcnt lgkmcnt(1)
	v_mfma_f32_32x32x16_bf16 v[0:15], v[156:159], v[128:131], v[0:15]
	ds_read_b128 v[136:139], v233 offset:46144
	v_exp_f32_e32 v156, v142
	v_exp_f32_e32 v157, v143
	v_cvt_pk_bf16_f32 v140, v246, v247
	v_cvt_pk_bf16_f32 v141, v248, v249
	v_cvt_pk_bf16_f32 v142, v190, v191
	v_cvt_pk_bf16_f32 v143, v156, v157
	s_waitcnt lgkmcnt(1)
	v_mfma_f32_32x32x16_bf16 v[48:63], v[132:135], v[128:131], v[48:63]
	ds_read_b128 v[152:155], v233 offset:50752
	v_add_f32_e64 v158, v212, v190
	v_add_f32_e64 v159, v213, v191
	v_add_f32_e64 v156, v214, v156
	v_add_f32_e64 v157, v215, v157
	v_pk_add_f32 v[190:191], v[210:211], v[248:249]
	v_pk_add_f32 v[150:151], v[150:151], v[246:247]
	v_pk_add_f32 v[146:147], v[146:147], v[198:199]
	v_pk_add_f32 v[192:193], v[216:217], v[242:243]
	v_pk_add_f32 v[148:149], v[148:149], v[244:245]
	v_pk_add_f32 v[144:145], v[144:145], v[196:197]
	s_waitcnt lgkmcnt(1)
	v_mfma_f32_32x32x16_bf16 v[32:47], v[136:139], v[128:131], v[32:47]
	v_add_f32_e64 v136, v144, v148
	v_add_f32_e64 v137, v145, v149
	v_add_f32_e64 v138, v192, v146
	v_add_f32_e64 v139, v193, v147
	v_add_f32_e64 v136, v190, v136
	v_add_f32_e64 v137, v191, v137
	v_pk_add_f32 v[138:139], v[150:151], v[138:139]
	v_pk_add_f32 v[136:137], v[156:157], v[136:137]
	v_pk_add_f32 v[138:139], v[158:159], v[138:139]
	ds_read_b128 v[132:135], v233 offset:36960
	v_pk_mov_b32 v[144:145], v[138:139], v[136:137] op_sel:[1,0]
	v_mov_b32_e32 v139, v137
	v_pk_add_f32 v[136:137], v[144:145], v[138:139]
	s_nop 0
	v_add_f32_e32 v136, v136, v137
	v_add_f32_e32 v216, v237, v136
	s_waitcnt lgkmcnt(1)
	v_mfma_f32_32x32x16_bf16 v[16:31], v[152:155], v[128:131], v[16:31]
	ds_read_b128 v[136:139], v233 offset:41568
	v_max3_f32 v128, v112, v113, v80
	v_max3_f32 v144, v114, v115, v81
	v_max3_f32 v145, v128, v82, v83
	s_waitcnt lgkmcnt(1)
	v_mfma_f32_32x32x16_bf16 v[0:15], v[132:135], v[140:143], v[0:15]
	ds_read_b128 v[128:131], v233 offset:46176
	v_max3_f32 v132, v145, v116, v117
	v_max3_f32 v133, v144, v118, v119
	v_max3_f32 v144, v132, v84, v85
	v_max3_f32 v145, v133, v86, v87
	s_waitcnt lgkmcnt(1)
	v_mfma_f32_32x32x16_bf16 v[48:63], v[136:139], v[140:143], v[48:63]
	ds_read_b128 v[132:135], v233 offset:50784
	v_max3_f32 v136, v144, v120, v121
	v_max3_f32 v137, v145, v122, v123
	v_max3_f32 v136, v136, v88, v89
	v_max3_f32 v137, v137, v90, v91
	s_waitcnt lgkmcnt(1)
	v_mfma_f32_32x32x16_bf16 v[32:47], v[128:131], v[140:143], v[32:47]
	v_max3_f32 v128, v136, v124, v125
	v_max3_f32 v129, v137, v126, v127
	v_max3_f32 v128, v128, v92, v93
	v_max3_f32 v129, v129, v94, v95
	s_waitcnt lgkmcnt(0)
	v_mfma_f32_32x32x16_bf16 v[16:31], v[132:135], v[140:143], v[16:31]
	v_max_f32_e32 v128, v128, v129
	v_mov_b32_e32 v129, v128
	s_nop 1
	v_permlane32_swap_b32_e32 v128, v129
	v_max_f32_e32 v128, v128, v129
	s_nop 0
	v_cmp_lt_f32_e32 vcc, s3, v128
	s_cbranch_vccz .LBB0_426
; __device__ __forceinline__ float fast_exp2(float x) { return __builtin_amdgcn_exp2f(x); }
; template <int DV, int PAR, bool KW = true, bool KL = true, bool VL = true>
; __device__ __forceinline__ void attn_iter_full(AttnState<DV>& S, int t, LAS unsigned char* lds) {
;     ...
;     if (__any(mx > 8.0f)) {
;         const float dl = fmaxf(mx, 0.f), alpha = fast_exp2(-dl);
;         S.mrun += dl; S.lsum *= alpha;
; #pragma unroll
;         for (int i = 0; i < 16; ++i) { sn0[i] -= dl; sn1[i] -= dl; S.negm[i] = -S.mrun; }
; #pragma unroll
;         for (int d = 0; d < NDB; ++d)
; #pragma unroll
;             for (int i = 0; i < 16; ++i) S.o[d][i] *= alpha;
;     }
	v_max_f32_e32 v64, v128, v128
	v_max_f32_e32 v65, 0, v64
	v_exp_f32_e64 v66, -v65
	v_add_f32_e32 v236, v236, v65
	v_xor_b32_e32 v64, 0x80000000, v236
	v_sub_f32_e32 v127, v127, v65
	v_mul_f32_e32 v216, v216, v66
	v_sub_f32_e32 v126, v126, v65
	v_sub_f32_e32 v125, v125, v65
	v_sub_f32_e32 v124, v124, v65
	v_sub_f32_e32 v123, v123, v65
	v_sub_f32_e32 v122, v122, v65
	v_sub_f32_e32 v121, v121, v65
	v_sub_f32_e32 v120, v120, v65
	v_sub_f32_e32 v119, v119, v65
	v_sub_f32_e32 v118, v118, v65
	v_sub_f32_e32 v117, v117, v65
	v_sub_f32_e32 v116, v116, v65
	v_sub_f32_e32 v115, v115, v65
	v_sub_f32_e32 v114, v114, v65
	v_sub_f32_e32 v113, v113, v65
	v_sub_f32_e32 v112, v112, v65
	v_sub_f32_e32 v95, v95, v65
	v_sub_f32_e32 v94, v94, v65
	v_sub_f32_e32 v93, v93, v65
	v_sub_f32_e32 v92, v92, v65
	v_sub_f32_e32 v91, v91, v65
	v_sub_f32_e32 v90, v90, v65
	v_sub_f32_e32 v89, v89, v65
	v_sub_f32_e32 v88, v88, v65
	v_sub_f32_e32 v87, v87, v65
	v_sub_f32_e32 v86, v86, v65
	v_sub_f32_e32 v85, v85, v65
	v_sub_f32_e32 v84, v84, v65
	v_sub_f32_e32 v83, v83, v65
	v_sub_f32_e32 v82, v82, v65
	v_sub_f32_e32 v81, v81, v65
	v_sub_f32_e32 v80, v80, v65
	v_pk_mul_f32 v[14:15], v[14:15], v[66:67] op_sel_hi:[1,0]
	v_pk_mul_f32 v[12:13], v[12:13], v[66:67] op_sel_hi:[1,0]
	v_pk_mul_f32 v[10:11], v[10:11], v[66:67] op_sel_hi:[1,0]
	v_pk_mul_f32 v[8:9], v[8:9], v[66:67] op_sel_hi:[1,0]
	v_pk_mul_f32 v[6:7], v[6:7], v[66:67] op_sel_hi:[1,0]
	v_pk_mul_f32 v[4:5], v[4:5], v[66:67] op_sel_hi:[1,0]
	v_pk_mul_f32 v[2:3], v[2:3], v[66:67] op_sel_hi:[1,0]
	v_pk_mul_f32 v[0:1], v[0:1], v[66:67] op_sel_hi:[1,0]
	v_pk_mul_f32 v[62:63], v[62:63], v[66:67] op_sel_hi:[1,0]
	v_pk_mul_f32 v[60:61], v[60:61], v[66:67] op_sel_hi:[1,0]
	v_pk_mul_f32 v[58:59], v[58:59], v[66:67] op_sel_hi:[1,0]
	v_pk_mul_f32 v[56:57], v[56:57], v[66:67] op_sel_hi:[1,0]
	v_pk_mul_f32 v[54:55], v[54:55], v[66:67] op_sel_hi:[1,0]
	v_pk_mul_f32 v[52:53], v[52:53], v[66:67] op_sel_hi:[1,0]
	v_pk_mul_f32 v[50:51], v[50:51], v[66:67] op_sel_hi:[1,0]
	v_pk_mul_f32 v[48:49], v[48:49], v[66:67] op_sel_hi:[1,0]
	v_pk_mul_f32 v[46:47], v[46:47], v[66:67] op_sel_hi:[1,0]
	v_pk_mul_f32 v[44:45], v[44:45], v[66:67] op_sel_hi:[1,0]
	v_pk_mul_f32 v[42:43], v[42:43], v[66:67] op_sel_hi:[1,0]
	v_pk_mul_f32 v[40:41], v[40:41], v[66:67] op_sel_hi:[1,0]
	v_pk_mul_f32 v[38:39], v[38:39], v[66:67] op_sel_hi:[1,0]
	v_pk_mul_f32 v[36:37], v[36:37], v[66:67] op_sel_hi:[1,0]
	v_pk_mul_f32 v[34:35], v[34:35], v[66:67] op_sel_hi:[1,0]
	v_pk_mul_f32 v[32:33], v[32:33], v[66:67] op_sel_hi:[1,0]
	v_pk_mul_f32 v[30:31], v[30:31], v[66:67] op_sel_hi:[1,0]
	v_pk_mul_f32 v[28:29], v[28:29], v[66:67] op_sel_hi:[1,0]
	v_pk_mul_f32 v[26:27], v[26:27], v[66:67] op_sel_hi:[1,0]
	v_pk_mul_f32 v[24:25], v[24:25], v[66:67] op_sel_hi:[1,0]
	v_pk_mul_f32 v[22:23], v[22:23], v[66:67] op_sel_hi:[1,0]
	v_pk_mul_f32 v[20:21], v[20:21], v[66:67] op_sel_hi:[1,0]
	v_pk_mul_f32 v[18:19], v[18:19], v[66:67] op_sel_hi:[1,0]
	v_pk_mul_f32 v[16:17], v[16:17], v[66:67] op_sel_hi:[1,0]
	v_mov_b32_e32 v65, v64
	v_mov_b32_e32 v66, v64
	v_mov_b32_e32 v67, v64
	v_mov_b32_e32 v68, v64
	v_mov_b32_e32 v69, v64
	v_mov_b32_e32 v70, v64
	v_mov_b32_e32 v71, v64
	v_mov_b32_e32 v72, v64
	v_mov_b32_e32 v73, v64
	v_mov_b32_e32 v74, v64
	v_mov_b32_e32 v75, v64
	v_mov_b32_e32 v76, v64
	v_mov_b32_e32 v77, v64
	v_mov_b32_e32 v78, v64
	v_mov_b32_e32 v79, v64
	v_mov_b32_e32 v96, v64
	v_mov_b32_e32 v97, v64
	v_mov_b32_e32 v98, v64
	v_mov_b32_e32 v99, v64
	v_mov_b32_e32 v100, v64
	v_mov_b32_e32 v101, v64
	v_mov_b32_e32 v102, v64
	v_mov_b32_e32 v103, v64
	v_mov_b32_e32 v104, v64
	v_mov_b32_e32 v105, v64
	v_mov_b32_e32 v106, v64
	v_mov_b32_e32 v107, v64
	v_mov_b32_e32 v108, v64
	v_mov_b32_e32 v109, v64
	v_mov_b32_e32 v110, v64
	v_mov_b32_e32 v111, v64
	s_branch .LBB0_426

;     __device__ bool next(int i, Unit& u) const { if (i > 0) return false; u.pm = pm; u.pn = pn; return true; }
; template <class Epi, class Sched, bool ALIGN_EPI = false, bool SP2 = false>
; __device__ __forceinline__ void gemm_phase(PG8_LAS unsigned char* lds, const Gemm g, const Sched& S, const Epi& E) {
;     ...
;         const bool has_next = S.next(ui + 1, nxt);
;         const char* nA = has_next ? (const char*)g.A + (size_t)nxt.pm * tstep : cA; const char* nB = has_next ? (const char*)g.Bt + (size_t)nxt.pn * tstep : cB;
;         for (int t = 0; t < nt; t += 2) {
;             const bool last = (t == nt - 2);
;             const char* a1 = cA + (size_t)(t + 1) * kstep;
;             const char* a2 = last ? nA : cA + (size_t)(t + 2) * kstep; const char* b2 = last ? nB : cB + (size_t)(t + 2) * kstep;
;     ...
; #pragma unroll
;         for (int a = 0; a < 2; ++a)
; #pragma unroll
;             for (int b = 0; b < 2; ++b)
; #pragma unroll
;                 for (int m = 0; m < 4; ++m)
; #pragma unroll
;                     for (int n = 0; n < 2; ++n) acc[a][b][m][n] = (f32x4){0.f, 0.f, 0.f, 0.f};
.LBB0_612:
	s_ashr_i32 s15, s14, 31
	s_lshl_b64 s[18:19], s[14:15], 19
	v_readlane_b32 s6, v254, 22
	v_readlane_b32 s7, v254, 23
	s_add_u32 s18, s6, s18
	s_addc_u32 s19, s7, s19
	s_and_b64 s[20:21], s[0:1], exec
	s_cselect_b32 s15, s19, s23
	s_cselect_b32 s38, s18, s22
	s_ashr_i32 s13, s12, 31
	s_lshl_b64 s[20:21], s[12:13], 19
	s_add_u32 s20, s40, s20
	s_addc_u32 s21, s41, s21
	s_and_b64 s[26:27], s[0:1], exec
	s_cselect_b32 s13, s21, s25
	s_cselect_b32 s39, s20, s24
	s_add_u32 s22, s22, 0x40080
	s_addc_u32 s23, s23, 0
	s_add_u32 s44, s24, 0x100
	s_addc_u32 s45, s25, 0
	s_mov_b32 s46, -2
	v_mov_b64_e32 v[0:1], 0
	v_mov_b64_e32 v[2:3], 0
	v_mov_b64_e32 v[4:5], 0
	v_mov_b64_e32 v[6:7], 0
	v_mov_b64_e32 v[8:9], 0
	v_mov_b64_e32 v[10:11], 0
	v_mov_b64_e32 v[12:13], 0
	v_mov_b64_e32 v[14:15], 0
	v_mov_b64_e32 v[16:17], 0
	v_mov_b64_e32 v[18:19], 0
	v_mov_b64_e32 v[20:21], 0
	v_mov_b64_e32 v[22:23], 0
	v_mov_b64_e32 v[24:25], 0
	v_mov_b64_e32 v[26:27], 0
	v_mov_b64_e32 v[28:29], 0
	v_mov_b64_e32 v[30:31], 0
	v_mov_b64_e32 v[32:33], 0
	v_mov_b64_e32 v[34:35], 0
	v_mov_b64_e32 v[36:37], 0
	v_mov_b64_e32 v[38:39], 0
	v_mov_b64_e32 v[40:41], 0
	v_mov_b64_e32 v[42:43], 0
	v_mov_b64_e32 v[44:45], 0
	v_mov_b64_e32 v[46:47], 0
	v_mov_b64_e32 v[48:49], 0
	v_mov_b64_e32 v[50:51], 0
	v_mov_b64_e32 v[52:53], 0
	v_mov_b64_e32 v[54:55], 0
	v_mov_b64_e32 v[56:57], 0
	v_mov_b64_e32 v[58:59], 0
	v_mov_b64_e32 v[60:61], 0
	v_mov_b64_e32 v[62:63], 0
	v_mov_b64_e32 v[64:65], 0
	v_mov_b64_e32 v[66:67], 0
	v_mov_b64_e32 v[68:69], 0
	v_mov_b64_e32 v[70:71], 0
	v_mov_b64_e32 v[72:73], 0
	v_mov_b64_e32 v[74:75], 0
	v_mov_b64_e32 v[76:77], 0
	v_mov_b64_e32 v[78:79], 0
	v_mov_b64_e32 v[80:81], 0
	v_mov_b64_e32 v[82:83], 0
	v_mov_b64_e32 v[84:85], 0
	v_mov_b64_e32 v[86:87], 0
	v_mov_b64_e32 v[88:89], 0
	v_mov_b64_e32 v[90:91], 0
	v_mov_b64_e32 v[92:93], 0
	v_mov_b64_e32 v[94:95], 0
	v_mov_b64_e32 v[96:97], 0
	v_mov_b64_e32 v[98:99], 0
	v_mov_b64_e32 v[100:101], 0
	v_mov_b64_e32 v[102:103], 0
	v_mov_b64_e32 v[104:105], 0
	v_mov_b64_e32 v[106:107], 0
	v_mov_b64_e32 v[108:109], 0
	v_mov_b64_e32 v[110:111], 0
	v_mov_b64_e32 v[112:113], 0
	v_mov_b64_e32 v[114:115], 0
	v_mov_b64_e32 v[116:117], 0
	v_mov_b64_e32 v[118:119], 0
	v_mov_b64_e32 v[120:121], 0
	v_mov_b64_e32 v[122:123], 0
	v_mov_b64_e32 v[124:125], 0
	v_mov_b64_e32 v[126:127], 0

; template <class Epi, class Sched, bool ALIGN_EPI = false, bool SP2 = false>
; __device__ __forceinline__ void gemm_phase(PG8_LAS unsigned char* lds, const Gemm g, const Sched& S, const Epi& E) {
;     ...
;         const char* nA = has_next ? (const char*)g.A + (size_t)nxt.pm * tstep : cA; const char* nB = has_next ? (const char*)g.Bt + (size_t)nxt.pn * tstep : cB;
;         for (int t = 0; t < nt; t += 2) {
;             const bool last = (t == nt - 2);
;             const char* a1 = cA + (size_t)(t + 1) * kstep;
;             const char* a2 = last ? nA : cA + (size_t)(t + 2) * kstep; const char* b2 = last ? nB : cB + (size_t)(t + 2) * kstep;
;             const char* a3 = a2 + kstep; const char* b3 = b2 + kstep;
;     ...
;         for (int a = 0; a < 2; ++a)
; #pragma unroll
;             for (int b = 0; b < 2; ++b)
; #pragma unroll
;                 for (int m = 0; m < 4; ++m)
; #pragma unroll
;                     for (int n = 0; n < 2; ++n) acc[a][b][m][n] = (f32x4){0.f, 0.f, 0.f, 0.f};
.LBB0_774:
	s_ashr_i32 s19, s18, 31
	s_lshl_b64 s[20:21], s[18:19], 19
	s_add_u32 s20, s60, s20
	s_addc_u32 s21, s61, s21
	s_and_b64 s[22:23], s[8:9], exec
	s_cselect_b32 s19, s21, s29
	s_cselect_b32 s25, s20, s28
	s_ashr_i32 s13, s12, 31
	s_lshl_b64 s[22:23], s[12:13], 19
	s_add_u32 s22, s36, s22
	s_addc_u32 s23, s33, s23
	s_and_b64 s[34:35], s[8:9], exec
	s_cselect_b32 s13, s23, s31
	s_cselect_b32 s68, s22, s30
	s_add_u32 s28, s28, 0x40080
	s_addc_u32 s29, s29, 0
	s_add_u32 s69, s30, 0x100
	s_addc_u32 s70, s31, 0
	s_mov_b32 s71, -2
	v_mov_b64_e32 v[0:1], 0
	v_mov_b64_e32 v[2:3], 0
	v_mov_b64_e32 v[4:5], 0
	v_mov_b64_e32 v[6:7], 0
	v_mov_b64_e32 v[8:9], 0
	v_mov_b64_e32 v[10:11], 0
	v_mov_b64_e32 v[12:13], 0
	v_mov_b64_e32 v[14:15], 0
	v_mov_b64_e32 v[16:17], 0
	v_mov_b64_e32 v[18:19], 0
	v_mov_b64_e32 v[20:21], 0
	v_mov_b64_e32 v[22:23], 0
	v_mov_b64_e32 v[24:25], 0
	v_mov_b64_e32 v[26:27], 0
	v_mov_b64_e32 v[28:29], 0
	v_mov_b64_e32 v[30:31], 0
	v_mov_b64_e32 v[32:33], 0
	v_mov_b64_e32 v[34:35], 0
	v_mov_b64_e32 v[36:37], 0
	v_mov_b64_e32 v[38:39], 0
	v_mov_b64_e32 v[40:41], 0
	v_mov_b64_e32 v[42:43], 0
	v_mov_b64_e32 v[44:45], 0
	v_mov_b64_e32 v[46:47], 0
	v_mov_b64_e32 v[48:49], 0
	v_mov_b64_e32 v[50:51], 0
	v_mov_b64_e32 v[52:53], 0
	v_mov_b64_e32 v[54:55], 0
	v_mov_b64_e32 v[56:57], 0
	v_mov_b64_e32 v[58:59], 0
	v_mov_b64_e32 v[60:61], 0
	v_mov_b64_e32 v[62:63], 0
	v_mov_b64_e32 v[64:65], 0
	v_mov_b64_e32 v[66:67], 0
	v_mov_b64_e32 v[68:69], 0
	v_mov_b64_e32 v[70:71], 0
	v_mov_b64_e32 v[72:73], 0
	v_mov_b64_e32 v[74:75], 0
	v_mov_b64_e32 v[76:77], 0
	v_mov_b64_e32 v[78:79], 0
	v_mov_b64_e32 v[80:81], 0
	v_mov_b64_e32 v[82:83], 0
	v_mov_b64_e32 v[84:85], 0
	v_mov_b64_e32 v[86:87], 0
	v_mov_b64_e32 v[88:89], 0
	v_mov_b64_e32 v[90:91], 0
	v_mov_b64_e32 v[92:93], 0
	v_mov_b64_e32 v[94:95], 0
	v_mov_b64_e32 v[96:97], 0
	v_mov_b64_e32 v[98:99], 0
	v_mov_b64_e32 v[100:101], 0
	v_mov_b64_e32 v[102:103], 0
	v_mov_b64_e32 v[104:105], 0
	v_mov_b64_e32 v[106:107], 0
	v_mov_b64_e32 v[108:109], 0
	v_mov_b64_e32 v[110:111], 0
	v_mov_b64_e32 v[112:113], 0
	v_mov_b64_e32 v[114:115], 0
	v_mov_b64_e32 v[116:117], 0
	v_mov_b64_e32 v[118:119], 0
	v_mov_b64_e32 v[120:121], 0
	v_mov_b64_e32 v[122:123], 0
	v_mov_b64_e32 v[124:125], 0
	v_mov_b64_e32 v[126:127], 0

; template <class Epi, class Sched, bool ALIGN_EPI = false, bool SP2 = false>
; __device__ __forceinline__ void gemm_phase(PG8_LAS unsigned char* lds, const Gemm g, const Sched& S, const Epi& E) {
;     ...
;         for (int a = 0; a < 2; ++a)
; #pragma unroll
;             for (int b = 0; b < 2; ++b)
; #pragma unroll
;                 for (int m = 0; m < 4; ++m)
; #pragma unroll
;                     for (int n = 0; n < 2; ++n) acc[a][b][m][n] = (f32x4){0.f, 0.f, 0.f, 0.f};
.LBB0_850:
	s_add_u32 s40, s18, 0x100
	s_addc_u32 s41, s19, 0
	s_mov_b32 s44, -2
	v_mov_b64_e32 v[0:1], 0
	v_mov_b64_e32 v[2:3], 0
	v_mov_b64_e32 v[4:5], 0
	v_mov_b64_e32 v[6:7], 0
	v_mov_b64_e32 v[8:9], 0
	v_mov_b64_e32 v[10:11], 0
	v_mov_b64_e32 v[12:13], 0
	v_mov_b64_e32 v[14:15], 0
	v_mov_b64_e32 v[16:17], 0
	v_mov_b64_e32 v[18:19], 0
	v_mov_b64_e32 v[20:21], 0
	v_mov_b64_e32 v[22:23], 0
	v_mov_b64_e32 v[24:25], 0
	v_mov_b64_e32 v[26:27], 0
	v_mov_b64_e32 v[28:29], 0
	v_mov_b64_e32 v[30:31], 0
	v_mov_b64_e32 v[32:33], 0
	v_mov_b64_e32 v[34:35], 0
	v_mov_b64_e32 v[36:37], 0
	v_mov_b64_e32 v[38:39], 0
	v_mov_b64_e32 v[40:41], 0
	v_mov_b64_e32 v[42:43], 0
	v_mov_b64_e32 v[44:45], 0
	v_mov_b64_e32 v[46:47], 0
	v_mov_b64_e32 v[48:49], 0
	v_mov_b64_e32 v[50:51], 0
	v_mov_b64_e32 v[52:53], 0
	v_mov_b64_e32 v[54:55], 0
	v_mov_b64_e32 v[56:57], 0
	v_mov_b64_e32 v[58:59], 0
	v_mov_b64_e32 v[60:61], 0
	v_mov_b64_e32 v[62:63], 0
	v_mov_b64_e32 v[64:65], 0
	v_mov_b64_e32 v[66:67], 0
	v_mov_b64_e32 v[68:69], 0
	v_mov_b64_e32 v[70:71], 0
	v_mov_b64_e32 v[72:73], 0
	v_mov_b64_e32 v[74:75], 0
	v_mov_b64_e32 v[76:77], 0
	v_mov_b64_e32 v[78:79], 0
	v_mov_b64_e32 v[80:81], 0
	v_mov_b64_e32 v[82:83], 0
	v_mov_b64_e32 v[84:85], 0
	v_mov_b64_e32 v[86:87], 0
	v_mov_b64_e32 v[88:89], 0
	v_mov_b64_e32 v[90:91], 0
	v_mov_b64_e32 v[92:93], 0
	v_mov_b64_e32 v[94:95], 0
	v_mov_b64_e32 v[96:97], 0
	v_mov_b64_e32 v[98:99], 0
	v_mov_b64_e32 v[100:101], 0
	v_mov_b64_e32 v[102:103], 0
	v_mov_b64_e32 v[104:105], 0
	v_mov_b64_e32 v[106:107], 0
	v_mov_b64_e32 v[108:109], 0
	v_mov_b64_e32 v[110:111], 0
	v_mov_b64_e32 v[112:113], 0
	v_mov_b64_e32 v[114:115], 0
	v_mov_b64_e32 v[116:117], 0
	v_mov_b64_e32 v[118:119], 0
	v_mov_b64_e32 v[120:121], 0
	v_mov_b64_e32 v[122:123], 0
	v_mov_b64_e32 v[124:125], 0
	v_mov_b64_e32 v[126:127], 0
